# speedup vs baseline: 1.0008x; 1.0008x over previous
; __device__ __forceinline__ void gmlp_item(PARAMS_T& p, int l, int b, int pos0, int tokrow0) {
;     ...
;   {
;     const int dim = tid >> 1, half = tid & 1;
;     const float gd = p.gm_v_g[l * 256 + dim];
;     const unsigned short* src = (const unsigned short*)(p.ws + OFF_VT) + ((size_t)b * 256 + dim) * PTOK + pos0 + half * 64;
; #pragma unroll
;     for (int i = 0; i < 8; ++i) {
;       u32x4 w = *reinterpret_cast<const u32x4*>(src + i * 8);
;       const int t0 = half * 64 + i * 8;
;       float f0 = __uint_as_float(w[0] << 16) * rs[t0 + 0] * gd, f1 = __uint_as_float(w[0] & 0xffff0000u) * rs[t0 + 1] * gd;
;       float f2 = __uint_as_float(w[1] << 16) * rs[t0 + 2] * gd, f3 = __uint_as_float(w[1] & 0xffff0000u) * rs[t0 + 3] * gd;
;       float f4 = __uint_as_float(w[2] << 16) * rs[t0 + 4] * gd, f5 = __uint_as_float(w[2] & 0xffff0000u) * rs[t0 + 5] * gd;
;       float f6 = __uint_as_float(w[3] << 16) * rs[t0 + 6] * gd, f7 = __uint_as_float(w[3] & 0xffff0000u) * rs[t0 + 7] * gd;
;       u32x4 o = {cvtpk(f0, f1), cvtpk(f2, f3), cvtpk(f4, f5), cvtpk(f6, f7)};
;       *reinterpret_cast<u32x4*>(Vn + dim * 136 + t0) = o;
;     }
;   }
.LBB0_825:
	s_or_b64 exec, exec, s[6:7]
	s_or_b32 s6, s9, 0x2000
	s_and_b64 s[4:5], s[4:5], exec
	v_ashrrev_i32_e32 v34, 1, v20
	s_cselect_b32 s6, s9, s6
	v_ashrrev_i32_e32 v35, 31, v34
	s_lshl_b64 s[4:5], s[88:89], 8
	v_lshl_add_u64 v[18:19], s[4:5], 0, v[34:35]
	v_readlane_b32 s4, v255, 34
	v_readlane_b32 s5, v255, 35
	s_movk_i32 s7, 0x4200
	v_lshlrev_b32_e32 v16, 6, v20
	v_mov_b64_e32 v[22:23], s[4:5]
	v_mad_u64_u32 v[22:23], s[4:5], v18, s7, v[22:23]
	v_mad_i32_i24 v23, v19, s7, v23
	s_lshl_b32 s88, s6, 1
	v_and_b32_e32 v21, 64, v16
	v_lshl_add_u64 v[18:19], v[22:23], 0, s[88:89]
	v_lshlrev_b32_e32 v16, 1, v21
	v_lshl_add_u64 v[18:19], v[18:19], 0, v[16:17]
	s_waitcnt lgkmcnt(0)
	s_barrier
	global_load_dwordx4 v[22:25], v[18:19], off
	s_load_dwordx2 s[6:7], s[86:87], 0x58
	s_load_dwordx2 s[4:5], s[86:87], 0x68
	v_lshl_add_u32 v36, v21, 2, 0
	v_ashrrev_i32_e32 v70, 7, v20
	v_ashrrev_i32_e32 v71, 31, v70
	s_waitcnt lgkmcnt(0)
	v_lshl_add_u64 v[26:27], v[34:35], 2, s[6:7]
	global_load_dword v35, v[26:27], off
	ds_read_b128 v[26:29], v36
	ds_read_b128 v[30:33], v36 offset:16
	s_movk_i32 s6, 0x110
	v_readlane_b32 s10, v255, 36
	v_bfe_u32 v73, v20, 5, 1
	v_bfe_u32 v76, v20, 6, 1
	v_readlane_b32 s11, v255, 37
	v_mov_b32_e32 v79, v17
	s_waitcnt vmcnt(1)
	v_lshlrev_b32_e32 v21, 16, v22
	v_and_b32_e32 v22, 0xffff0000, v22
	v_lshlrev_b32_e32 v37, 16, v23
	v_and_b32_e32 v23, 0xffff0000, v23
	v_lshlrev_b32_e32 v38, 16, v24
	v_and_b32_e32 v24, 0xffff0000, v24
	v_lshlrev_b32_e32 v39, 16, v25
	v_and_b32_e32 v25, 0xffff0000, v25
	s_waitcnt lgkmcnt(1)
	v_mul_f32_e32 v21, v26, v21
	v_mul_f32_e32 v22, v27, v22
	v_mul_f32_e32 v26, v28, v37
	v_mul_f32_e32 v23, v29, v23
	s_waitcnt lgkmcnt(0)
	v_mul_f32_e32 v27, v30, v38
	v_mul_f32_e32 v24, v31, v24
	v_mul_f32_e32 v28, v32, v39
	v_mul_f32_e32 v25, v33, v25
	s_waitcnt vmcnt(0)
	v_mul_f32_e32 v22, v35, v22
	v_mul_f32_e32 v26, v35, v26
	v_mul_f32_e32 v23, v35, v23
	v_mul_f32_e32 v27, v35, v27
	v_mul_f32_e32 v24, v35, v24
	v_mul_f32_e32 v28, v35, v28
	v_mul_f32_e32 v25, v35, v25
	v_mul_f32_e32 v21, v35, v21
	v_cvt_pk_bf16_f32 v22, v21, v22
	v_cvt_pk_bf16_f32 v23, v26, v23
	v_cvt_pk_bf16_f32 v24, v27, v24
	v_cvt_pk_bf16_f32 v25, v28, v25
	global_load_dwordx4 v[26:29], v[18:19], off offset:16
	v_mul_lo_u32 v21, v34, s6
	v_add3_u32 v34, 0, v21, v16
	ds_write_b128 v34, v[22:25] offset:1024
	ds_read_b128 v[22:25], v36 offset:32
	ds_read_b128 v[30:33], v36 offset:48
	s_waitcnt vmcnt(0)
	v_lshlrev_b32_e32 v16, 16, v26
	v_and_b32_e32 v21, 0xffff0000, v26
	v_lshlrev_b32_e32 v26, 16, v27
	v_and_b32_e32 v27, 0xffff0000, v27
	v_lshlrev_b32_e32 v37, 16, v28
	v_and_b32_e32 v28, 0xffff0000, v28
	v_lshlrev_b32_e32 v38, 16, v29
	v_and_b32_e32 v29, 0xffff0000, v29
	s_waitcnt lgkmcnt(1)
	v_mul_f32_e32 v16, v22, v16
	v_mul_f32_e32 v21, v23, v21
	v_mul_f32_e32 v22, v24, v26
	v_mul_f32_e32 v23, v25, v27
	s_waitcnt lgkmcnt(0)
	v_mul_f32_e32 v24, v30, v37
	v_mul_f32_e32 v25, v31, v28
	v_mul_f32_e32 v26, v32, v38
	v_mul_f32_e32 v27, v33, v29
	v_mul_f32_e32 v28, v35, v22
	v_mul_f32_e32 v23, v35, v23
	v_mul_f32_e32 v24, v35, v24
	v_mul_f32_e32 v25, v35, v25
	v_mul_f32_e32 v26, v35, v26
	v_mul_f32_e32 v27, v35, v27
	v_mul_f32_e32 v16, v35, v16
	v_mul_f32_e32 v21, v35, v21
	v_cvt_pk_bf16_f32 v22, v16, v21
	v_cvt_pk_bf16_f32 v23, v28, v23
	v_cvt_pk_bf16_f32 v24, v24, v25
	v_cvt_pk_bf16_f32 v25, v26, v27
	global_load_dwordx4 v[26:29], v[18:19], off offset:32
	ds_write_b128 v34, v[22:25] offset:1040
	ds_read_b128 v[22:25], v36 offset:64
	ds_read_b128 v[30:33], v36 offset:80
	s_waitcnt vmcnt(0)
	v_lshlrev_b32_e32 v16, 16, v26
	v_and_b32_e32 v21, 0xffff0000, v26
	v_lshlrev_b32_e32 v26, 16, v27
	v_and_b32_e32 v27, 0xffff0000, v27
	v_lshlrev_b32_e32 v37, 16, v28
	v_and_b32_e32 v28, 0xffff0000, v28
	v_lshlrev_b32_e32 v38, 16, v29
	v_and_b32_e32 v29, 0xffff0000, v29
	s_waitcnt lgkmcnt(1)
	v_mul_f32_e32 v16, v22, v16
	v_mul_f32_e32 v21, v23, v21
	v_mul_f32_e32 v22, v24, v26
	v_mul_f32_e32 v23, v25, v27
	s_waitcnt lgkmcnt(0)
	v_mul_f32_e32 v24, v30, v37
	v_mul_f32_e32 v25, v31, v28
	v_mul_f32_e32 v26, v32, v38
	v_mul_f32_e32 v27, v33, v29
	v_mul_f32_e32 v28, v35, v22
	v_mul_f32_e32 v23, v35, v23
	v_mul_f32_e32 v24, v35, v24
	v_mul_f32_e32 v25, v35, v25
	v_mul_f32_e32 v26, v35, v26
	v_mul_f32_e32 v27, v35, v27
	v_mul_f32_e32 v16, v35, v16
	v_mul_f32_e32 v21, v35, v21
	v_cvt_pk_bf16_f32 v22, v16, v21
	v_cvt_pk_bf16_f32 v23, v28, v23
	v_cvt_pk_bf16_f32 v24, v24, v25
	v_cvt_pk_bf16_f32 v25, v26, v27
	global_load_dwordx4 v[26:29], v[18:19], off offset:48
	ds_write_b128 v34, v[22:25] offset:1056
	ds_read_b128 v[22:25], v36 offset:96
	ds_read_b128 v[30:33], v36 offset:112
	s_waitcnt vmcnt(0)
	v_lshlrev_b32_e32 v16, 16, v26
	v_and_b32_e32 v21, 0xffff0000, v26
	v_lshlrev_b32_e32 v26, 16, v27
	v_and_b32_e32 v27, 0xffff0000, v27
	v_lshlrev_b32_e32 v37, 16, v28
	v_and_b32_e32 v28, 0xffff0000, v28
	v_lshlrev_b32_e32 v38, 16, v29
	v_and_b32_e32 v29, 0xffff0000, v29
	s_waitcnt lgkmcnt(1)
	v_mul_f32_e32 v16, v22, v16
	v_mul_f32_e32 v21, v23, v21
	v_mul_f32_e32 v22, v24, v26
	v_mul_f32_e32 v23, v25, v27
	s_waitcnt lgkmcnt(0)
	v_mul_f32_e32 v24, v30, v37
	v_mul_f32_e32 v25, v31, v28
	v_mul_f32_e32 v26, v32, v38
	v_mul_f32_e32 v27, v33, v29
	v_mul_f32_e32 v28, v35, v22
	v_mul_f32_e32 v23, v35, v23
	v_mul_f32_e32 v24, v35, v24
	v_mul_f32_e32 v25, v35, v25
	v_mul_f32_e32 v26, v35, v26
	v_mul_f32_e32 v27, v35, v27
	v_mul_f32_e32 v16, v35, v16
	v_mul_f32_e32 v21, v35, v21
	v_cvt_pk_bf16_f32 v22, v16, v21
	v_cvt_pk_bf16_f32 v23, v28, v23
	v_cvt_pk_bf16_f32 v24, v24, v25
	v_cvt_pk_bf16_f32 v25, v26, v27
	global_load_dwordx4 v[26:29], v[18:19], off offset:64
	ds_write_b128 v34, v[22:25] offset:1072
	ds_read_b128 v[22:25], v36 offset:128
	ds_read_b128 v[30:33], v36 offset:144
	s_waitcnt vmcnt(0)
; __device__ __forceinline__ void gmlp_item(PARAMS_T& p, int l, int b, int pos0, int tokrow0) {
;     ...
;     for (int i = 0; i < 8; ++i) {
;       u32x4 w = *reinterpret_cast<const u32x4*>(src + i * 8);
;       const int t0 = half * 64 + i * 8;
;       float f0 = __uint_as_float(w[0] << 16) * rs[t0 + 0] * gd, f1 = __uint_as_float(w[0] & 0xffff0000u) * rs[t0 + 1] * gd;
;       float f2 = __uint_as_float(w[1] << 16) * rs[t0 + 2] * gd, f3 = __uint_as_float(w[1] & 0xffff0000u) * rs[t0 + 3] * gd;
;       float f4 = __uint_as_float(w[2] << 16) * rs[t0 + 4] * gd, f5 = __uint_as_float(w[2] & 0xffff0000u) * rs[t0 + 5] * gd;
;       float f6 = __uint_as_float(w[3] << 16) * rs[t0 + 6] * gd, f7 = __uint_as_float(w[3] & 0xffff0000u) * rs[t0 + 7] * gd;
;       u32x4 o = {cvtpk(f0, f1), cvtpk(f2, f3), cvtpk(f4, f5), cvtpk(f6, f7)};
;       *reinterpret_cast<u32x4*>(Vn + dim * 136 + t0) = o;
;     }
;   }
;   __syncthreads();
	v_lshlrev_b32_e32 v16, 16, v26
	v_and_b32_e32 v21, 0xffff0000, v26
	v_lshlrev_b32_e32 v26, 16, v27
	v_and_b32_e32 v27, 0xffff0000, v27
	v_lshlrev_b32_e32 v37, 16, v28
	v_and_b32_e32 v28, 0xffff0000, v28
	v_lshlrev_b32_e32 v38, 16, v29
	v_and_b32_e32 v29, 0xffff0000, v29
	s_waitcnt lgkmcnt(1)
	v_mul_f32_e32 v16, v22, v16
	v_mul_f32_e32 v21, v23, v21
	v_mul_f32_e32 v22, v24, v26
	v_mul_f32_e32 v23, v25, v27
	s_waitcnt lgkmcnt(0)
	v_mul_f32_e32 v24, v30, v37
	v_mul_f32_e32 v25, v31, v28
	v_mul_f32_e32 v26, v32, v38
	v_mul_f32_e32 v27, v33, v29
	v_mul_f32_e32 v28, v35, v22
	v_mul_f32_e32 v23, v35, v23
	v_mul_f32_e32 v24, v35, v24
	v_mul_f32_e32 v25, v35, v25
	v_mul_f32_e32 v26, v35, v26
	v_mul_f32_e32 v27, v35, v27
	v_mul_f32_e32 v16, v35, v16
	v_mul_f32_e32 v21, v35, v21
	v_cvt_pk_bf16_f32 v22, v16, v21
	v_cvt_pk_bf16_f32 v23, v28, v23
	v_cvt_pk_bf16_f32 v24, v24, v25
	v_cvt_pk_bf16_f32 v25, v26, v27
	global_load_dwordx4 v[26:29], v[18:19], off offset:80
	ds_write_b128 v34, v[22:25] offset:1088
	ds_read_b128 v[22:25], v36 offset:160
	ds_read_b128 v[30:33], v36 offset:176
	s_waitcnt vmcnt(0)
	v_lshlrev_b32_e32 v16, 16, v26
	v_and_b32_e32 v21, 0xffff0000, v26
	v_lshlrev_b32_e32 v26, 16, v27
	v_and_b32_e32 v27, 0xffff0000, v27
	v_lshlrev_b32_e32 v37, 16, v28
	v_and_b32_e32 v28, 0xffff0000, v28
	v_lshlrev_b32_e32 v38, 16, v29
	v_and_b32_e32 v29, 0xffff0000, v29
	s_waitcnt lgkmcnt(1)
	v_mul_f32_e32 v16, v22, v16
	v_mul_f32_e32 v21, v23, v21
	v_mul_f32_e32 v22, v24, v26
	v_mul_f32_e32 v23, v25, v27
	s_waitcnt lgkmcnt(0)
	v_mul_f32_e32 v24, v30, v37
	v_mul_f32_e32 v25, v31, v28
	v_mul_f32_e32 v26, v32, v38
	v_mul_f32_e32 v27, v33, v29
	v_mul_f32_e32 v28, v35, v22
	v_mul_f32_e32 v23, v35, v23
	v_mul_f32_e32 v24, v35, v24
	v_mul_f32_e32 v25, v35, v25
	v_mul_f32_e32 v26, v35, v26
	v_mul_f32_e32 v27, v35, v27
	v_mul_f32_e32 v16, v35, v16
	v_mul_f32_e32 v21, v35, v21
	v_cvt_pk_bf16_f32 v22, v16, v21
	v_cvt_pk_bf16_f32 v23, v28, v23
	v_cvt_pk_bf16_f32 v24, v24, v25
	v_cvt_pk_bf16_f32 v25, v26, v27
	global_load_dwordx4 v[26:29], v[18:19], off offset:96
	ds_write_b128 v34, v[22:25] offset:1104
	ds_read_b128 v[22:25], v36 offset:192
	ds_read_b128 v[30:33], v36 offset:208
	s_waitcnt vmcnt(0)
	v_lshlrev_b32_e32 v16, 16, v26
	v_and_b32_e32 v21, 0xffff0000, v26
	v_lshlrev_b32_e32 v26, 16, v27
	v_and_b32_e32 v27, 0xffff0000, v27
	v_lshlrev_b32_e32 v37, 16, v28
	v_and_b32_e32 v28, 0xffff0000, v28
	v_lshlrev_b32_e32 v38, 16, v29
	v_and_b32_e32 v29, 0xffff0000, v29
	s_waitcnt lgkmcnt(1)
	v_mul_f32_e32 v16, v22, v16
	v_mul_f32_e32 v21, v23, v21
	v_mul_f32_e32 v22, v24, v26
	v_mul_f32_e32 v23, v25, v27
	s_waitcnt lgkmcnt(0)
	v_mul_f32_e32 v24, v30, v37
	v_mul_f32_e32 v25, v31, v28
	v_mul_f32_e32 v26, v32, v38
	v_mul_f32_e32 v27, v33, v29
	v_mul_f32_e32 v28, v35, v22
	v_mul_f32_e32 v23, v35, v23
	v_mul_f32_e32 v24, v35, v24
	v_mul_f32_e32 v25, v35, v25
	v_mul_f32_e32 v26, v35, v26
	v_mul_f32_e32 v27, v35, v27
	v_mul_f32_e32 v16, v35, v16
	v_mul_f32_e32 v21, v35, v21
	v_cvt_pk_bf16_f32 v22, v16, v21
	v_cvt_pk_bf16_f32 v23, v28, v23
	v_cvt_pk_bf16_f32 v24, v24, v25
	v_cvt_pk_bf16_f32 v25, v26, v27
	global_load_dwordx4 v[26:29], v[18:19], off offset:112
	v_and_b32_e32 v30, 31, v20
	v_lshlrev_b32_e32 v16, 8, v30
	v_lshlrev_b64 v[18:19], 15, v[70:71]
	v_lshl_or_b32 v78, v76, 14, v16
	v_lshl_add_u64 v[18:19], s[10:11], 0, v[18:19]
	v_lshlrev_b32_e32 v16, 4, v73
	ds_write_b128 v34, v[22:25] offset:1120
	v_lshl_add_u64 v[80:81], v[18:19], 0, v[16:17]
	ds_read_b128 v[18:21], v36 offset:224
	ds_read_b128 v[22:25], v36 offset:240
	v_lshl_add_u64 v[74:75], v[80:81], 0, v[78:79]
	v_lshl_or_b32 v72, v70, 6, v30
	v_lshlrev_b64 v[70:71], 9, v[70:71]
	s_waitcnt vmcnt(0)
	v_lshlrev_b32_e32 v31, 16, v26
	v_and_b32_e32 v26, 0xffff0000, v26
	v_lshlrev_b32_e32 v32, 16, v27
	v_and_b32_e32 v27, 0xffff0000, v27
	v_lshlrev_b32_e32 v33, 16, v28
	v_and_b32_e32 v28, 0xffff0000, v28
	v_lshlrev_b32_e32 v36, 16, v29
	v_and_b32_e32 v29, 0xffff0000, v29
	s_waitcnt lgkmcnt(1)
	v_mul_f32_e32 v18, v18, v31
	v_mul_f32_e32 v19, v19, v26
	v_mul_f32_e32 v20, v20, v32
	v_mul_f32_e32 v21, v21, v27
	s_waitcnt lgkmcnt(0)
	v_mul_f32_e32 v22, v22, v33
	v_mul_f32_e32 v23, v23, v28
	v_mul_f32_e32 v24, v24, v36
	v_mul_f32_e32 v25, v25, v29
	v_mul_f32_e32 v18, v35, v18
	v_mul_f32_e32 v19, v35, v19
	v_mul_f32_e32 v20, v35, v20
	v_mul_f32_e32 v21, v35, v21
	v_mul_f32_e32 v22, v35, v22
	v_mul_f32_e32 v23, v35, v23
	v_mul_f32_e32 v24, v35, v24
	v_mul_f32_e32 v25, v35, v25
	v_cvt_pk_bf16_f32 v18, v18, v19
	v_cvt_pk_bf16_f32 v19, v20, v21
	v_cvt_pk_bf16_f32 v20, v22, v23
	v_cvt_pk_bf16_f32 v21, v24, v25
	ds_write_b128 v34, v[18:21] offset:1136
	s_waitcnt lgkmcnt(0)
	s_barrier
; __device__ __forceinline__ void gmlp_item(PARAMS_T& p, int l, int b, int pos0, int tokrow0) {
;     ...
;   const int g = wid >> 1, th = wid & 1;
;   const bf16* wsb = (const bf16*)(p.ws + OFF_WSBF) + ((size_t)l * 4 + g) * 128 * 128;
;   f32x16 acc[2][2] = {};
; #pragma unroll
;   for (int ks = 0; ks < 8; ++ks) {
;     bf16x8 af[2], bfr[2];
; #pragma unroll
;     for (int tb = 0; tb < 2; ++tb) af[tb] = *reinterpret_cast<const bf16x8*>(wsb + (size_t)(th * 64 + tb * 32 + r32) * 128 + ks * 16 + hi * 8);
; #pragma unroll
;     for (int db = 0; db < 2; ++db) bfr[db] = *reinterpret_cast<const bf16x8*>(Vn + (g * 64 + db * 32 + r32) * 136 + ks * 16 + hi * 8);
; #pragma unroll
;     for (int tb = 0; tb < 2; ++tb)
; #pragma unroll
;       for (int db = 0; db < 2; ++db) acc[tb][db] = __builtin_amdgcn_mfma_f32_32x32x16_bf16(af[tb], bfr[db], acc[tb][db], 0, 0, 0);
;   }
	v_and_b32_e32 v250, 31, v192
	v_bfe_u32 v251, v192, 5, 1
	v_lshrrev_b32_e32 v252, 7, v192
	v_bfe_u32 v253, v192, 6, 1
	v_lshl_or_b32 v254, v252, 6, v250
	v_lshlrev_b32_e32 v172, 1, v254
	v_mul_u32_u24_e32 v254, 0x110, v254
	v_lshl_add_u32 v254, v251, 4, v254
	v_add_u32_e32 v16, 0x400, v254
	v_lshl_or_b32 v254, v253, 6, v250
	v_lshlrev_b32_e32 v254, 8, v254
	v_lshl_or_b32 v254, v251, 4, v254
	v_lshl_add_u32 v254, v252, 15, v254
	v_mov_b32_e32 v162, v254
	v_mov_b32_e32 v163, 0
	v_lshl_add_u64 v[162:163], s[10:11], 0, v[162:163]
	v_mov_b32_e32 v164, 0x2000
	v_mov_b32_e32 v165, 0
	v_lshl_add_u64 v[164:165], v[162:163], 0, v[164:165]
	global_load_dwordx4 v[82:85], v[162:163], off
	global_load_dwordx4 v[86:89], v[164:165], off
	global_load_dwordx4 v[90:93], v[162:163], off offset:32
	global_load_dwordx4 v[94:97], v[164:165], off offset:32
	global_load_dwordx4 v[98:101], v[162:163], off offset:64
	global_load_dwordx4 v[102:105], v[164:165], off offset:64
	global_load_dwordx4 v[106:109], v[162:163], off offset:96
	global_load_dwordx4 v[110:113], v[164:165], off offset:96
	global_load_dwordx4 v[114:117], v[162:163], off offset:128
	global_load_dwordx4 v[118:121], v[164:165], off offset:128
	global_load_dwordx4 v[122:125], v[162:163], off offset:160
	global_load_dwordx4 v[126:129], v[164:165], off offset:160
	global_load_dwordx4 v[130:133], v[162:163], off offset:192
	global_load_dwordx4 v[134:137], v[164:165], off offset:192
	global_load_dwordx4 v[138:141], v[162:163], off offset:224
	global_load_dwordx4 v[142:145], v[164:165], off offset:224
	v_lshlrev_b32_e32 v171, 6, v253
	v_lshl_add_u32 v171, v251, 2, v171
	v_lshl_add_u32 v170, v252, 7, v171
	v_lshlrev_b32_e32 v170, 2, v170
	v_add_u32_e32 v171, s8, v171
	v_add_u32_e32 v254, 0, v171
	v_lshl_add_u32 v162, v254, 9, v172
	v_add_u32_e32 v254, 8, v171
	v_lshl_add_u32 v163, v254, 9, v172
	v_add_u32_e32 v254, 16, v171
	v_lshl_add_u32 v164, v254, 9, v172
	v_add_u32_e32 v254, 24, v171
	v_lshl_add_u32 v165, v254, 9, v172
	v_add_u32_e32 v254, 32, v171
	v_lshl_add_u32 v166, v254, 9, v172
	v_add_u32_e32 v254, 40, v171
	v_lshl_add_u32 v167, v254, 9, v172
	v_add_u32_e32 v254, 48, v171
	v_lshl_add_u32 v168, v254, 9, v172
	v_add_u32_e32 v254, 56, v171
	v_lshl_add_u32 v169, v254, 9, v172
	v_mov_b32_e32 v18, 0
	v_mov_b32_e32 v19, 0
	v_mov_b32_e32 v20, 0
	v_mov_b32_e32 v21, 0
	v_mov_b32_e32 v22, 0
	v_mov_b32_e32 v23, 0
	v_mov_b32_e32 v24, 0
	v_mov_b32_e32 v25, 0
	v_mov_b32_e32 v26, 0
	v_mov_b32_e32 v27, 0
	v_mov_b32_e32 v28, 0
	v_mov_b32_e32 v29, 0
	v_mov_b32_e32 v30, 0
	v_mov_b32_e32 v31, 0
	v_mov_b32_e32 v32, 0
	v_mov_b32_e32 v33, 0
	v_mov_b32_e32 v34, 0
	v_mov_b32_e32 v35, 0
	v_mov_b32_e32 v36, 0
	v_mov_b32_e32 v37, 0
	v_mov_b32_e32 v38, 0
	v_mov_b32_e32 v39, 0
	v_mov_b32_e32 v40, 0
	v_mov_b32_e32 v41, 0
	v_mov_b32_e32 v42, 0
	v_mov_b32_e32 v43, 0
	v_mov_b32_e32 v44, 0
	v_mov_b32_e32 v45, 0
	v_mov_b32_e32 v46, 0
	v_mov_b32_e32 v47, 0
	v_mov_b32_e32 v48, 0
	v_mov_b32_e32 v49, 0
	v_mov_b32_e32 v50, 0
	v_mov_b32_e32 v51, 0
	v_mov_b32_e32 v52, 0
	v_mov_b32_e32 v53, 0
	v_mov_b32_e32 v54, 0
	v_mov_b32_e32 v55, 0
	v_mov_b32_e32 v56, 0
	v_mov_b32_e32 v57, 0
	v_mov_b32_e32 v58, 0
	v_mov_b32_e32 v59, 0
	v_mov_b32_e32 v60, 0
	v_mov_b32_e32 v61, 0
	v_mov_b32_e32 v62, 0
	v_mov_b32_e32 v63, 0
	v_mov_b32_e32 v64, 0
	v_mov_b32_e32 v65, 0
	v_mov_b32_e32 v66, 0
	v_mov_b32_e32 v67, 0
	v_mov_b32_e32 v68, 0
	v_mov_b32_e32 v69, 0
	v_mov_b32_e32 v70, 0
	v_mov_b32_e32 v71, 0
	v_mov_b32_e32 v72, 0
	v_mov_b32_e32 v73, 0
	v_mov_b32_e32 v74, 0
	v_mov_b32_e32 v75, 0
	v_mov_b32_e32 v76, 0
	v_mov_b32_e32 v77, 0
	v_mov_b32_e32 v78, 0
	v_mov_b32_e32 v79, 0
	v_mov_b32_e32 v80, 0
	v_mov_b32_e32 v81, 0
	ds_read_b128 v[146:149], v16 offset:0
	ds_read_b128 v[150:153], v16 offset:8704
	ds_read_b128 v[154:157], v16 offset:32
	ds_read_b128 v[158:161], v16 offset:8736
	ds_read_b128 v[234:237], v16 offset:64
	ds_read_b128 v[238:241], v16 offset:8768
	ds_read_b128 v[242:245], v16 offset:96
	ds_read_b128 v[246:249], v16 offset:8800
	s_waitcnt vmcnt(15) lgkmcnt(7)
	v_mfma_f32_32x32x16_bf16 v[18:33], v[82:85], v[146:149], v[18:33]
	s_waitcnt vmcnt(15) lgkmcnt(6)
	v_mfma_f32_32x32x16_bf16 v[34:49], v[82:85], v[150:153], v[34:49]
	s_waitcnt vmcnt(14)
	v_mfma_f32_32x32x16_bf16 v[50:65], v[86:89], v[146:149], v[50:65]
	v_mfma_f32_32x32x16_bf16 v[66:81], v[86:89], v[150:153], v[66:81]
	s_waitcnt vmcnt(13) lgkmcnt(5)
	v_mfma_f32_32x32x16_bf16 v[18:33], v[90:93], v[154:157], v[18:33]
	s_waitcnt vmcnt(13) lgkmcnt(4)
	v_mfma_f32_32x32x16_bf16 v[34:49], v[90:93], v[158:161], v[34:49]
	s_waitcnt vmcnt(12)
	v_mfma_f32_32x32x16_bf16 v[50:65], v[94:97], v[154:157], v[50:65]
	v_mfma_f32_32x32x16_bf16 v[66:81], v[94:97], v[158:161], v[66:81]
	s_waitcnt vmcnt(11) lgkmcnt(3)
	v_mfma_f32_32x32x16_bf16 v[18:33], v[98:101], v[234:237], v[18:33]
	s_waitcnt vmcnt(11) lgkmcnt(2)
	v_mfma_f32_32x32x16_bf16 v[34:49], v[98:101], v[238:241], v[34:49]
	s_waitcnt vmcnt(10)
	v_mfma_f32_32x32x16_bf16 v[50:65], v[102:105], v[234:237], v[50:65]
	v_mfma_f32_32x32x16_bf16 v[66:81], v[102:105], v[238:241], v[66:81]
	s_waitcnt vmcnt(9) lgkmcnt(1)
	v_mfma_f32_32x32x16_bf16 v[18:33], v[106:109], v[242:245], v[18:33]
	s_waitcnt vmcnt(9) lgkmcnt(0)
	v_mfma_f32_32x32x16_bf16 v[34:49], v[106:109], v[246:249], v[34:49]
	s_waitcnt vmcnt(8)
	v_mfma_f32_32x32x16_bf16 v[50:65], v[110:113], v[242:245], v[50:65]
	v_mfma_f32_32x32x16_bf16 v[66:81], v[110:113], v[246:249], v[66:81]
	ds_read_b128 v[146:149], v16 offset:128
	ds_read_b128 v[150:153], v16 offset:8832
	ds_read_b128 v[154:157], v16 offset:160
	ds_read_b128 v[158:161], v16 offset:8864
	ds_read_b128 v[234:237], v16 offset:192
	ds_read_b128 v[238:241], v16 offset:8896
	ds_read_b128 v[242:245], v16 offset:224
	ds_read_b128 v[246:249], v16 offset:8928
	s_waitcnt vmcnt(7) lgkmcnt(7)
; __device__ __forceinline__ unsigned short bf1(float a) { return (unsigned short)(cvtpk(a, 0.f) & 0xffffu); }
; __device__ __forceinline__ int crow(int r, int hi) { return (r & 3) + 8 * (r >> 2) + 4 * hi; }
; __device__ __forceinline__ void gmlp_item(PARAMS_T& p, int l, int b, int pos0, int tokrow0) {
;     ...
; #pragma unroll
;   for (int ks = 0; ks < 8; ++ks) {
;     bf16x8 af[2], bfr[2];
; #pragma unroll
;     for (int tb = 0; tb < 2; ++tb) af[tb] = *reinterpret_cast<const bf16x8*>(wsb + (size_t)(th * 64 + tb * 32 + r32) * 128 + ks * 16 + hi * 8);
; #pragma unroll
;     for (int db = 0; db < 2; ++db) bfr[db] = *reinterpret_cast<const bf16x8*>(Vn + (g * 64 + db * 32 + r32) * 136 + ks * 16 + hi * 8);
; #pragma unroll
;     for (int tb = 0; tb < 2; ++tb)
; #pragma unroll
;       for (int db = 0; db < 2; ++db) acc[tb][db] = __builtin_amdgcn_mfma_f32_32x32x16_bf16(af[tb], bfr[db], acc[tb][db], 0, 0, 0);
;   }
;   const float* bs = p.gm_bs + ((size_t)l * 4 + g) * 128;
;   const unsigned short* u = (const unsigned short*)(p.ws + OFF_U);
;   unsigned short* outp = (unsigned short*)(p.ws + OFF_ACTA);
; #pragma unroll
;   for (int tb = 0; tb < 2; ++tb)
; #pragma unroll
;     for (int r = 0; r < 16; ++r) {
;       const int t = th * 64 + tb * 32 + crow(r, hi);
;       const float bt = bs[t];
; #pragma unroll
;       for (int db = 0; db < 2; ++db) {
;         const int d = g * 64 + db * 32 + r32;
;         const float uv = __uint_as_float(((unsigned)u[(size_t)(tokrow0 + t) * 256 + d]) << 16);
;         outp[(size_t)(tokrow0 + t) * 1024 + 256 + d] = bf1(uv * (acc[tb][db][r] + bt));
;       }
;     }
	v_mfma_f32_32x32x16_bf16 v[18:33], v[114:117], v[146:149], v[18:33]
	s_waitcnt vmcnt(7) lgkmcnt(6)
	v_mfma_f32_32x32x16_bf16 v[34:49], v[114:117], v[150:153], v[34:49]
	s_waitcnt vmcnt(6)
	v_mfma_f32_32x32x16_bf16 v[50:65], v[118:121], v[146:149], v[50:65]
	v_mfma_f32_32x32x16_bf16 v[66:81], v[118:121], v[150:153], v[66:81]
	s_waitcnt vmcnt(5) lgkmcnt(5)
	v_mfma_f32_32x32x16_bf16 v[18:33], v[122:125], v[154:157], v[18:33]
	s_waitcnt vmcnt(5) lgkmcnt(4)
	v_mfma_f32_32x32x16_bf16 v[34:49], v[122:125], v[158:161], v[34:49]
	s_waitcnt vmcnt(4)
	v_mfma_f32_32x32x16_bf16 v[50:65], v[126:129], v[154:157], v[50:65]
	v_mfma_f32_32x32x16_bf16 v[66:81], v[126:129], v[158:161], v[66:81]
	s_waitcnt vmcnt(3) lgkmcnt(3)
	v_mfma_f32_32x32x16_bf16 v[18:33], v[130:133], v[234:237], v[18:33]
	s_waitcnt vmcnt(3) lgkmcnt(2)
	v_mfma_f32_32x32x16_bf16 v[34:49], v[130:133], v[238:241], v[34:49]
	s_waitcnt vmcnt(2)
	v_mfma_f32_32x32x16_bf16 v[50:65], v[134:137], v[234:237], v[50:65]
	v_mfma_f32_32x32x16_bf16 v[66:81], v[134:137], v[238:241], v[66:81]
	s_waitcnt vmcnt(1) lgkmcnt(1)
	v_mfma_f32_32x32x16_bf16 v[18:33], v[138:141], v[242:245], v[18:33]
	s_waitcnt vmcnt(1) lgkmcnt(0)
	v_mfma_f32_32x32x16_bf16 v[34:49], v[138:141], v[246:249], v[34:49]
	s_waitcnt vmcnt(0)
	v_mfma_f32_32x32x16_bf16 v[50:65], v[142:145], v[242:245], v[50:65]
	v_mfma_f32_32x32x16_bf16 v[66:81], v[142:145], v[246:249], v[66:81]
	global_load_dwordx4 v[146:149], v170, s[4:5]
	global_load_ushort v82, v162, s[80:81]
	global_load_ushort v83, v162, s[80:81] offset:64
	global_load_ushort v84, v162, s[80:81] offset:512
	global_load_ushort v85, v162, s[80:81] offset:576
	global_load_ushort v86, v162, s[80:81] offset:1024
	global_load_ushort v87, v162, s[80:81] offset:1088
	global_load_ushort v88, v162, s[80:81] offset:1536
	global_load_ushort v89, v162, s[80:81] offset:1600
	global_load_dwordx4 v[150:153], v170, s[4:5] offset:32
	global_load_ushort v90, v163, s[80:81]
	global_load_ushort v91, v163, s[80:81] offset:64
	global_load_ushort v92, v163, s[80:81] offset:512
	global_load_ushort v93, v163, s[80:81] offset:576
	global_load_ushort v94, v163, s[80:81] offset:1024
	global_load_ushort v95, v163, s[80:81] offset:1088
	global_load_ushort v96, v163, s[80:81] offset:1536
	global_load_ushort v97, v163, s[80:81] offset:1600
	global_load_dwordx4 v[154:157], v170, s[4:5] offset:64
	global_load_ushort v98, v164, s[80:81]
	global_load_ushort v99, v164, s[80:81] offset:64
	global_load_ushort v100, v164, s[80:81] offset:512
	global_load_ushort v101, v164, s[80:81] offset:576
	global_load_ushort v102, v164, s[80:81] offset:1024
	global_load_ushort v103, v164, s[80:81] offset:1088
	global_load_ushort v104, v164, s[80:81] offset:1536
	global_load_ushort v105, v164, s[80:81] offset:1600
	global_load_dwordx4 v[158:161], v170, s[4:5] offset:96
	global_load_ushort v106, v165, s[80:81]
	global_load_ushort v107, v165, s[80:81] offset:64
	global_load_ushort v108, v165, s[80:81] offset:512
	global_load_ushort v109, v165, s[80:81] offset:576
	global_load_ushort v110, v165, s[80:81] offset:1024
	global_load_ushort v111, v165, s[80:81] offset:1088
	global_load_ushort v112, v165, s[80:81] offset:1536
	global_load_ushort v113, v165, s[80:81] offset:1600
	global_load_dwordx4 v[234:237], v170, s[4:5] offset:128
	global_load_ushort v114, v166, s[80:81]
	global_load_ushort v115, v166, s[80:81] offset:64
	global_load_ushort v116, v166, s[80:81] offset:512
	global_load_ushort v117, v166, s[80:81] offset:576
	global_load_ushort v118, v166, s[80:81] offset:1024
	global_load_ushort v119, v166, s[80:81] offset:1088
	global_load_ushort v120, v166, s[80:81] offset:1536
	global_load_ushort v121, v166, s[80:81] offset:1600
	global_load_dwordx4 v[238:241], v170, s[4:5] offset:160
	global_load_ushort v122, v167, s[80:81]
	global_load_ushort v123, v167, s[80:81] offset:64
	global_load_ushort v124, v167, s[80:81] offset:512
	global_load_ushort v125, v167, s[80:81] offset:576
	global_load_ushort v126, v167, s[80:81] offset:1024
	global_load_ushort v127, v167, s[80:81] offset:1088
	global_load_ushort v128, v167, s[80:81] offset:1536
	global_load_ushort v129, v167, s[80:81] offset:1600
	global_load_dwordx4 v[242:245], v170, s[4:5] offset:192
	global_load_ushort v130, v168, s[80:81]
	global_load_ushort v131, v168, s[80:81] offset:64
	global_load_ushort v132, v168, s[80:81] offset:512
	global_load_ushort v133, v168, s[80:81] offset:576
	global_load_ushort v134, v168, s[80:81] offset:1024
	global_load_ushort v135, v168, s[80:81] offset:1088
	global_load_ushort v136, v168, s[80:81] offset:1536
	global_load_ushort v137, v168, s[80:81] offset:1600
	global_load_dwordx4 v[246:249], v170, s[4:5] offset:224
	global_load_ushort v138, v169, s[80:81]
	global_load_ushort v139, v169, s[80:81] offset:64
	global_load_ushort v140, v169, s[80:81] offset:512
	global_load_ushort v141, v169, s[80:81] offset:576
	global_load_ushort v142, v169, s[80:81] offset:1024
	global_load_ushort v143, v169, s[80:81] offset:1088
	global_load_ushort v144, v169, s[80:81] offset:1536
	global_load_ushort v145, v169, s[80:81] offset:1600
	s_waitcnt vmcnt(63)
	v_add_f32_e32 v250, v18, v146
	v_lshlrev_b32_e32 v82, 16, v82
	v_mul_f32_e32 v82, v250, v82
	v_cvt_pk_bf16_f32 v82, v82, v17
	v_add_f32_e32 v251, v34, v146
	v_lshlrev_b32_e32 v83, 16, v83
	v_mul_f32_e32 v83, v251, v83
	v_cvt_pk_bf16_f32 v83, v83, v17
	s_waitcnt vmcnt(63)
	v_add_f32_e32 v250, v19, v147
	v_lshlrev_b32_e32 v84, 16, v84
	v_mul_f32_e32 v84, v250, v84
	v_cvt_pk_bf16_f32 v84, v84, v17
	v_add_f32_e32 v251, v35, v147
	v_lshlrev_b32_e32 v85, 16, v85
	v_mul_f32_e32 v85, v251, v85
	v_cvt_pk_bf16_f32 v85, v85, v17
	s_waitcnt vmcnt(63)
; __device__ __forceinline__ unsigned short bf1(float a) { return (unsigned short)(cvtpk(a, 0.f) & 0xffffu); }
; __device__ __forceinline__ int crow(int r, int hi) { return (r & 3) + 8 * (r >> 2) + 4 * hi; }
; __device__ __forceinline__ void gmlp_item(PARAMS_T& p, int l, int b, int pos0, int tokrow0) {
;     ...
; #pragma unroll
;   for (int tb = 0; tb < 2; ++tb)
; #pragma unroll
;     for (int r = 0; r < 16; ++r) {
;       const int t = th * 64 + tb * 32 + crow(r, hi);
;       const float bt = bs[t];
; #pragma unroll
;       for (int db = 0; db < 2; ++db) {
;         const int d = g * 64 + db * 32 + r32;
;         const float uv = __uint_as_float(((unsigned)u[(size_t)(tokrow0 + t) * 256 + d]) << 16);
;         outp[(size_t)(tokrow0 + t) * 1024 + 256 + d] = bf1(uv * (acc[tb][db][r] + bt));
;       }
;     }
	v_add_f32_e32 v250, v20, v148
	v_lshlrev_b32_e32 v86, 16, v86
	v_mul_f32_e32 v86, v250, v86
	v_cvt_pk_bf16_f32 v86, v86, v17
	v_add_f32_e32 v251, v36, v148
	v_lshlrev_b32_e32 v87, 16, v87
	v_mul_f32_e32 v87, v251, v87
	v_cvt_pk_bf16_f32 v87, v87, v17
	s_waitcnt vmcnt(63)
	v_add_f32_e32 v250, v21, v149
	v_lshlrev_b32_e32 v88, 16, v88
	v_mul_f32_e32 v88, v250, v88
	v_cvt_pk_bf16_f32 v88, v88, v17
	v_add_f32_e32 v251, v37, v149
	v_lshlrev_b32_e32 v89, 16, v89
	v_mul_f32_e32 v89, v251, v89
	v_cvt_pk_bf16_f32 v89, v89, v17
	s_waitcnt vmcnt(60)
	v_add_f32_e32 v250, v22, v150
	v_lshlrev_b32_e32 v90, 16, v90
	v_mul_f32_e32 v90, v250, v90
	v_cvt_pk_bf16_f32 v90, v90, v17
	v_add_f32_e32 v251, v38, v150
	v_lshlrev_b32_e32 v91, 16, v91
	v_mul_f32_e32 v91, v251, v91
	v_cvt_pk_bf16_f32 v91, v91, v17
	s_waitcnt vmcnt(58)
	v_add_f32_e32 v250, v23, v151
	v_lshlrev_b32_e32 v92, 16, v92
	v_mul_f32_e32 v92, v250, v92
	v_cvt_pk_bf16_f32 v92, v92, v17
	v_add_f32_e32 v251, v39, v151
	v_lshlrev_b32_e32 v93, 16, v93
	v_mul_f32_e32 v93, v251, v93
	v_cvt_pk_bf16_f32 v93, v93, v17
	s_waitcnt vmcnt(56)
	v_add_f32_e32 v250, v24, v152
	v_lshlrev_b32_e32 v94, 16, v94
	v_mul_f32_e32 v94, v250, v94
	v_cvt_pk_bf16_f32 v94, v94, v17
	v_add_f32_e32 v251, v40, v152
	v_lshlrev_b32_e32 v95, 16, v95
	v_mul_f32_e32 v95, v251, v95
	v_cvt_pk_bf16_f32 v95, v95, v17
	s_waitcnt vmcnt(54)
	v_add_f32_e32 v250, v25, v153
	v_lshlrev_b32_e32 v96, 16, v96
	v_mul_f32_e32 v96, v250, v96
	v_cvt_pk_bf16_f32 v96, v96, v17
	v_add_f32_e32 v251, v41, v153
	v_lshlrev_b32_e32 v97, 16, v97
	v_mul_f32_e32 v97, v251, v97
	v_cvt_pk_bf16_f32 v97, v97, v17
	s_waitcnt vmcnt(51)
	v_add_f32_e32 v250, v26, v154
	v_lshlrev_b32_e32 v98, 16, v98
	v_mul_f32_e32 v98, v250, v98
	v_cvt_pk_bf16_f32 v98, v98, v17
	v_add_f32_e32 v251, v42, v154
	v_lshlrev_b32_e32 v99, 16, v99
	v_mul_f32_e32 v99, v251, v99
	v_cvt_pk_bf16_f32 v99, v99, v17
	s_waitcnt vmcnt(49)
	v_add_f32_e32 v250, v27, v155
	v_lshlrev_b32_e32 v100, 16, v100
	v_mul_f32_e32 v100, v250, v100
	v_cvt_pk_bf16_f32 v100, v100, v17
	v_add_f32_e32 v251, v43, v155
	v_lshlrev_b32_e32 v101, 16, v101
	v_mul_f32_e32 v101, v251, v101
	v_cvt_pk_bf16_f32 v101, v101, v17
	s_waitcnt vmcnt(47)
	v_add_f32_e32 v250, v28, v156
	v_lshlrev_b32_e32 v102, 16, v102
	v_mul_f32_e32 v102, v250, v102
	v_cvt_pk_bf16_f32 v102, v102, v17
	v_add_f32_e32 v251, v44, v156
	v_lshlrev_b32_e32 v103, 16, v103
	v_mul_f32_e32 v103, v251, v103
	v_cvt_pk_bf16_f32 v103, v103, v17
	s_waitcnt vmcnt(45)
	v_add_f32_e32 v250, v29, v157
	v_lshlrev_b32_e32 v104, 16, v104
	v_mul_f32_e32 v104, v250, v104
	v_cvt_pk_bf16_f32 v104, v104, v17
	v_add_f32_e32 v251, v45, v157
	v_lshlrev_b32_e32 v105, 16, v105
	v_mul_f32_e32 v105, v251, v105
	v_cvt_pk_bf16_f32 v105, v105, v17
	s_waitcnt vmcnt(42)
	v_add_f32_e32 v250, v30, v158
	v_lshlrev_b32_e32 v106, 16, v106
	v_mul_f32_e32 v106, v250, v106
	v_cvt_pk_bf16_f32 v106, v106, v17
	v_add_f32_e32 v251, v46, v158
	v_lshlrev_b32_e32 v107, 16, v107
	v_mul_f32_e32 v107, v251, v107
	v_cvt_pk_bf16_f32 v107, v107, v17
	s_waitcnt vmcnt(40)
	v_add_f32_e32 v250, v31, v159
	v_lshlrev_b32_e32 v108, 16, v108
	v_mul_f32_e32 v108, v250, v108
	v_cvt_pk_bf16_f32 v108, v108, v17
	v_add_f32_e32 v251, v47, v159
	v_lshlrev_b32_e32 v109, 16, v109
	v_mul_f32_e32 v109, v251, v109
	v_cvt_pk_bf16_f32 v109, v109, v17
	s_waitcnt vmcnt(38)
	v_add_f32_e32 v250, v32, v160
	v_lshlrev_b32_e32 v110, 16, v110
	v_mul_f32_e32 v110, v250, v110
	v_cvt_pk_bf16_f32 v110, v110, v17
	v_add_f32_e32 v251, v48, v160
	v_lshlrev_b32_e32 v111, 16, v111
	v_mul_f32_e32 v111, v251, v111
	v_cvt_pk_bf16_f32 v111, v111, v17
	s_waitcnt vmcnt(36)
	v_add_f32_e32 v250, v33, v161
	v_lshlrev_b32_e32 v112, 16, v112
	v_mul_f32_e32 v112, v250, v112
	v_cvt_pk_bf16_f32 v112, v112, v17
	v_add_f32_e32 v251, v49, v161
	v_lshlrev_b32_e32 v113, 16, v113
	v_mul_f32_e32 v113, v251, v113
	v_cvt_pk_bf16_f32 v113, v113, v17
	s_waitcnt vmcnt(33)
	v_add_f32_e32 v250, v50, v234
	v_lshlrev_b32_e32 v114, 16, v114
	v_mul_f32_e32 v114, v250, v114
	v_cvt_pk_bf16_f32 v114, v114, v17
	v_add_f32_e32 v251, v66, v234
	v_lshlrev_b32_e32 v115, 16, v115
	v_mul_f32_e32 v115, v251, v115
	v_cvt_pk_bf16_f32 v115, v115, v17
	s_waitcnt vmcnt(31)
	v_add_f32_e32 v250, v51, v235
	v_lshlrev_b32_e32 v116, 16, v116
	v_mul_f32_e32 v116, v250, v116
	v_cvt_pk_bf16_f32 v116, v116, v17
	v_add_f32_e32 v251, v67, v235
	v_lshlrev_b32_e32 v117, 16, v117
	v_mul_f32_e32 v117, v251, v117
	v_cvt_pk_bf16_f32 v117, v117, v17
	s_waitcnt vmcnt(29)
	v_add_f32_e32 v250, v52, v236
	v_lshlrev_b32_e32 v118, 16, v118
	v_mul_f32_e32 v118, v250, v118
	v_cvt_pk_bf16_f32 v118, v118, v17
	v_add_f32_e32 v251, v68, v236
	v_lshlrev_b32_e32 v119, 16, v119
	v_mul_f32_e32 v119, v251, v119
	v_cvt_pk_bf16_f32 v119, v119, v17
	s_waitcnt vmcnt(27)
	v_add_f32_e32 v250, v53, v237
	v_lshlrev_b32_e32 v120, 16, v120
	v_mul_f32_e32 v120, v250, v120
	v_cvt_pk_bf16_f32 v120, v120, v17
	v_add_f32_e32 v251, v69, v237
	v_lshlrev_b32_e32 v121, 16, v121
	v_mul_f32_e32 v121, v251, v121
	v_cvt_pk_bf16_f32 v121, v121, v17
	s_waitcnt vmcnt(24)
	v_add_f32_e32 v250, v54, v238
	v_lshlrev_b32_e32 v122, 16, v122
	v_mul_f32_e32 v122, v250, v122
	v_cvt_pk_bf16_f32 v122, v122, v17
	v_add_f32_e32 v251, v70, v238
	v_lshlrev_b32_e32 v123, 16, v123
	v_mul_f32_e32 v123, v251, v123
	v_cvt_pk_bf16_f32 v123, v123, v17
	s_waitcnt vmcnt(22)
	v_add_f32_e32 v250, v55, v239
	v_lshlrev_b32_e32 v124, 16, v124
	v_mul_f32_e32 v124, v250, v124
	v_cvt_pk_bf16_f32 v124, v124, v17
	v_add_f32_e32 v251, v71, v239
	v_lshlrev_b32_e32 v125, 16, v125
	v_mul_f32_e32 v125, v251, v125
	v_cvt_pk_bf16_f32 v125, v125, v17
	s_waitcnt vmcnt(20)
; __device__ __forceinline__ unsigned short bf1(float a) { return (unsigned short)(cvtpk(a, 0.f) & 0xffffu); }
; __device__ __forceinline__ int crow(int r, int hi) { return (r & 3) + 8 * (r >> 2) + 4 * hi; }
; __device__ __forceinline__ void gmlp_item(PARAMS_T& p, int l, int b, int pos0, int tokrow0) {
;     ...
; #pragma unroll
;   for (int tb = 0; tb < 2; ++tb)
; #pragma unroll
;     for (int r = 0; r < 16; ++r) {
;       const int t = th * 64 + tb * 32 + crow(r, hi);
;       const float bt = bs[t];
; #pragma unroll
;       for (int db = 0; db < 2; ++db) {
;         const int d = g * 64 + db * 32 + r32;
;         const float uv = __uint_as_float(((unsigned)u[(size_t)(tokrow0 + t) * 256 + d]) << 16);
;         outp[(size_t)(tokrow0 + t) * 1024 + 256 + d] = bf1(uv * (acc[tb][db][r] + bt));
;       }
;     }
	v_add_f32_e32 v250, v56, v240
	v_lshlrev_b32_e32 v126, 16, v126
	v_mul_f32_e32 v126, v250, v126
	v_cvt_pk_bf16_f32 v126, v126, v17
	v_add_f32_e32 v251, v72, v240
	v_lshlrev_b32_e32 v127, 16, v127
	v_mul_f32_e32 v127, v251, v127
	v_cvt_pk_bf16_f32 v127, v127, v17
	s_waitcnt vmcnt(18)
	v_add_f32_e32 v250, v57, v241
	v_lshlrev_b32_e32 v128, 16, v128
	v_mul_f32_e32 v128, v250, v128
	v_cvt_pk_bf16_f32 v128, v128, v17
	v_add_f32_e32 v251, v73, v241
	v_lshlrev_b32_e32 v129, 16, v129
	v_mul_f32_e32 v129, v251, v129
	v_cvt_pk_bf16_f32 v129, v129, v17
	s_waitcnt vmcnt(15)
	v_add_f32_e32 v250, v58, v242
	v_lshlrev_b32_e32 v130, 16, v130
	v_mul_f32_e32 v130, v250, v130
	v_cvt_pk_bf16_f32 v130, v130, v17
	v_add_f32_e32 v251, v74, v242
	v_lshlrev_b32_e32 v131, 16, v131
	v_mul_f32_e32 v131, v251, v131
	v_cvt_pk_bf16_f32 v131, v131, v17
	s_waitcnt vmcnt(13)
	v_add_f32_e32 v250, v59, v243
	v_lshlrev_b32_e32 v132, 16, v132
	v_mul_f32_e32 v132, v250, v132
	v_cvt_pk_bf16_f32 v132, v132, v17
	v_add_f32_e32 v251, v75, v243
	v_lshlrev_b32_e32 v133, 16, v133
	v_mul_f32_e32 v133, v251, v133
	v_cvt_pk_bf16_f32 v133, v133, v17
	s_waitcnt vmcnt(11)
	v_add_f32_e32 v250, v60, v244
	v_lshlrev_b32_e32 v134, 16, v134
	v_mul_f32_e32 v134, v250, v134
	v_cvt_pk_bf16_f32 v134, v134, v17
	v_add_f32_e32 v251, v76, v244
	v_lshlrev_b32_e32 v135, 16, v135
	v_mul_f32_e32 v135, v251, v135
	v_cvt_pk_bf16_f32 v135, v135, v17
	s_waitcnt vmcnt(9)
	v_add_f32_e32 v250, v61, v245
	v_lshlrev_b32_e32 v136, 16, v136
	v_mul_f32_e32 v136, v250, v136
	v_cvt_pk_bf16_f32 v136, v136, v17
	v_add_f32_e32 v251, v77, v245
	v_lshlrev_b32_e32 v137, 16, v137
	v_mul_f32_e32 v137, v251, v137
	v_cvt_pk_bf16_f32 v137, v137, v17
	s_waitcnt vmcnt(6)
	v_add_f32_e32 v250, v62, v246
	v_lshlrev_b32_e32 v138, 16, v138
	v_mul_f32_e32 v138, v250, v138
	v_cvt_pk_bf16_f32 v138, v138, v17
	v_add_f32_e32 v251, v78, v246
	v_lshlrev_b32_e32 v139, 16, v139
	v_mul_f32_e32 v139, v251, v139
	v_cvt_pk_bf16_f32 v139, v139, v17
	s_waitcnt vmcnt(4)
	v_add_f32_e32 v250, v63, v247
	v_lshlrev_b32_e32 v140, 16, v140
	v_mul_f32_e32 v140, v250, v140
	v_cvt_pk_bf16_f32 v140, v140, v17
	v_add_f32_e32 v251, v79, v247
	v_lshlrev_b32_e32 v141, 16, v141
	v_mul_f32_e32 v141, v251, v141
	v_cvt_pk_bf16_f32 v141, v141, v17
	s_waitcnt vmcnt(2)
	v_add_f32_e32 v250, v64, v248
	v_lshlrev_b32_e32 v142, 16, v142
	v_mul_f32_e32 v142, v250, v142
	v_cvt_pk_bf16_f32 v142, v142, v17
	v_add_f32_e32 v251, v80, v248
	v_lshlrev_b32_e32 v143, 16, v143
	v_mul_f32_e32 v143, v251, v143
	v_cvt_pk_bf16_f32 v143, v143, v17
	s_waitcnt vmcnt(0)
	v_add_f32_e32 v250, v65, v249
	v_lshlrev_b32_e32 v144, 16, v144
	v_mul_f32_e32 v144, v250, v144
	v_cvt_pk_bf16_f32 v144, v144, v17
	v_add_f32_e32 v251, v81, v249
	v_lshlrev_b32_e32 v145, 16, v145
	v_mul_f32_e32 v145, v251, v145
	v_cvt_pk_bf16_f32 v145, v145, v17
	v_add_u32_e32 v254, 0, v171
	v_lshl_add_u32 v146, v254, 11, v172
	v_add_u32_e32 v254, 2, v171
	v_lshl_add_u32 v147, v254, 11, v172
	v_add_u32_e32 v254, 8, v171
	v_lshl_add_u32 v148, v254, 11, v172
	v_add_u32_e32 v254, 10, v171
	v_lshl_add_u32 v149, v254, 11, v172
	v_add_u32_e32 v254, 16, v171
	v_lshl_add_u32 v150, v254, 11, v172
	v_add_u32_e32 v254, 18, v171
	v_lshl_add_u32 v151, v254, 11, v172
	v_add_u32_e32 v254, 24, v171
	v_lshl_add_u32 v152, v254, 11, v172
	v_add_u32_e32 v254, 26, v171
	v_lshl_add_u32 v153, v254, 11, v172
	v_add_u32_e32 v254, 32, v171
	v_lshl_add_u32 v154, v254, 11, v172
	v_add_u32_e32 v254, 34, v171
	v_lshl_add_u32 v155, v254, 11, v172
	v_add_u32_e32 v254, 40, v171
	v_lshl_add_u32 v156, v254, 11, v172
	v_add_u32_e32 v254, 42, v171
	v_lshl_add_u32 v157, v254, 11, v172
	v_add_u32_e32 v254, 48, v171
	v_lshl_add_u32 v158, v254, 11, v172
	v_add_u32_e32 v254, 50, v171
	v_lshl_add_u32 v159, v254, 11, v172
	v_add_u32_e32 v254, 56, v171
	v_lshl_add_u32 v160, v254, 11, v172
	v_add_u32_e32 v254, 58, v171
	v_lshl_add_u32 v161, v254, 11, v172
	global_store_short v146, v82, s[0:1]
	global_store_short v146, v83, s[0:1] offset:64
	global_store_short v146, v84, s[0:1] offset:2048
	global_store_short v146, v85, s[0:1] offset:2112
	global_store_short v147, v86, s[0:1]
	global_store_short v147, v87, s[0:1] offset:64
	global_store_short v147, v88, s[0:1] offset:2048
	global_store_short v147, v89, s[0:1] offset:2112
	global_store_short v148, v90, s[0:1]
	global_store_short v148, v91, s[0:1] offset:64
	global_store_short v148, v92, s[0:1] offset:2048
	global_store_short v148, v93, s[0:1] offset:2112
	global_store_short v149, v94, s[0:1]
	global_store_short v149, v95, s[0:1] offset:64
	global_store_short v149, v96, s[0:1] offset:2048
	global_store_short v149, v97, s[0:1] offset:2112
	global_store_short v150, v98, s[0:1]
	global_store_short v150, v99, s[0:1] offset:64
	global_store_short v150, v100, s[0:1] offset:2048
	global_store_short v150, v101, s[0:1] offset:2112
	global_store_short v151, v102, s[0:1]
	global_store_short v151, v103, s[0:1] offset:64
	global_store_short v151, v104, s[0:1] offset:2048
	global_store_short v151, v105, s[0:1] offset:2112
	global_store_short v152, v106, s[0:1]
	global_store_short v152, v107, s[0:1] offset:64
	global_store_short v152, v108, s[0:1] offset:2048
	global_store_short v152, v109, s[0:1] offset:2112
	global_store_short v153, v110, s[0:1]
	global_store_short v153, v111, s[0:1] offset:64
	global_store_short v153, v112, s[0:1] offset:2048
	global_store_short v153, v113, s[0:1] offset:2112
	global_store_short v154, v114, s[0:1]
	global_store_short v154, v115, s[0:1] offset:64
	global_store_short v154, v116, s[0:1] offset:2048
	global_store_short v154, v117, s[0:1] offset:2112
	global_store_short v155, v118, s[0:1]
	global_store_short v155, v119, s[0:1] offset:64
	global_store_short v155, v120, s[0:1] offset:2048
	global_store_short v155, v121, s[0:1] offset:2112
	global_store_short v156, v122, s[0:1]
	global_store_short v156, v123, s[0:1] offset:64
	global_store_short v156, v124, s[0:1] offset:2048
	global_store_short v156, v125, s[0:1] offset:2112
	global_store_short v157, v126, s[0:1]
	global_store_short v157, v127, s[0:1] offset:64
	global_store_short v157, v128, s[0:1] offset:2048
	global_store_short v157, v129, s[0:1] offset:2112
	global_store_short v158, v130, s[0:1]
	global_store_short v158, v131, s[0:1] offset:64
	global_store_short v158, v132, s[0:1] offset:2048
	global_store_short v158, v133, s[0:1] offset:2112
	global_store_short v159, v134, s[0:1]
	global_store_short v159, v135, s[0:1] offset:64
	global_store_short v159, v136, s[0:1] offset:2048
	global_store_short v159, v137, s[0:1] offset:2112
	global_store_short v160, v138, s[0:1]
	global_store_short v160, v139, s[0:1] offset:64
	global_store_short v160, v140, s[0:1] offset:2048
	global_store_short v160, v141, s[0:1] offset:2112
	global_store_short v161, v142, s[0:1]
	global_store_short v161, v143, s[0:1] offset:64
	global_store_short v161, v144, s[0:1] offset:2048
	global_store_short v161, v145, s[0:1] offset:2112
	s_mov_b64 s[4:5], 0

; __device__ __forceinline__ void gmlp_item(PARAMS_T& p, int l, int b, int pos0, int tokrow0) {
;     ...
;   __syncthreads();
;   {
;     const int dim = tid >> 1, half = tid & 1;
;     const float gd = p.gm_v_g[l * 256 + dim];
;     const unsigned short* src = (const unsigned short*)(p.ws + OFF_VT) + ((size_t)b * 256 + dim) * PTOK + pos0 + half * 64;
; #pragma unroll
;     for (int i = 0; i < 8; ++i) {
;       u32x4 w = *reinterpret_cast<const u32x4*>(src + i * 8);
;       const int t0 = half * 64 + i * 8;
;       float f0 = __uint_as_float(w[0] << 16) * rs[t0 + 0] * gd, f1 = __uint_as_float(w[0] & 0xffff0000u) * rs[t0 + 1] * gd;
;       float f2 = __uint_as_float(w[1] << 16) * rs[t0 + 2] * gd, f3 = __uint_as_float(w[1] & 0xffff0000u) * rs[t0 + 3] * gd;
;       float f4 = __uint_as_float(w[2] << 16) * rs[t0 + 4] * gd, f5 = __uint_as_float(w[2] & 0xffff0000u) * rs[t0 + 5] * gd;
;       float f6 = __uint_as_float(w[3] << 16) * rs[t0 + 6] * gd, f7 = __uint_as_float(w[3] & 0xffff0000u) * rs[t0 + 7] * gd;
;       u32x4 o = {cvtpk(f0, f1), cvtpk(f2, f3), cvtpk(f4, f5), cvtpk(f6, f7)};
;       *reinterpret_cast<u32x4*>(Vn + dim * 136 + t0) = o;
;     }
;   }
.LBB0_1887:
	s_or_b64 exec, exec, s[6:7]
	v_ashrrev_i32_e32 v34, 1, v20
	v_ashrrev_i32_e32 v35, 31, v34
	s_lshl_b64 s[6:7], s[80:81], 8
	v_lshl_add_u64 v[18:19], s[6:7], 0, v[34:35]
	v_readlane_b32 s6, v255, 24
	v_readlane_b32 s7, v255, 25
	s_movk_i32 s5, 0x4200
	v_lshlrev_b32_e32 v16, 6, v20
	v_mov_b64_e32 v[22:23], s[6:7]
	v_mad_u64_u32 v[22:23], s[6:7], v18, s5, v[22:23]
	v_mad_i32_i24 v23, v19, s5, v23
	s_lshl_b32 s80, s4, 1
	v_and_b32_e32 v21, 64, v16
	v_lshl_add_u64 v[18:19], v[22:23], 0, s[80:81]
	v_lshlrev_b32_e32 v16, 1, v21
	v_lshl_add_u64 v[18:19], v[18:19], 0, v[16:17]
	s_waitcnt lgkmcnt(0)
	s_barrier
	global_load_dwordx4 v[22:25], v[18:19], off
	s_load_dwordx2 s[4:5], s[0:1], 0x58
	s_load_dwordx2 s[6:7], s[0:1], 0x68
	v_lshl_add_u32 v36, v21, 2, 0
	v_readlane_b32 s8, v255, 38
	v_bfe_u32 v73, v20, 5, 1
	s_waitcnt lgkmcnt(0)
	v_lshl_add_u64 v[26:27], v[34:35], 2, s[4:5]
	global_load_dword v35, v[26:27], off offset:1024
	ds_read_b128 v[26:29], v36
	ds_read_b128 v[30:33], v36 offset:16
	s_movk_i32 s4, 0x110
	v_bfe_u32 v76, v20, 6, 1
	v_readlane_b32 s9, v255, 39
	v_mov_b32_e32 v79, v17
	s_waitcnt vmcnt(1)
	v_lshlrev_b32_e32 v21, 16, v22
	v_and_b32_e32 v22, 0xffff0000, v22
	v_lshlrev_b32_e32 v37, 16, v23
	v_and_b32_e32 v23, 0xffff0000, v23
	v_lshlrev_b32_e32 v38, 16, v24
	v_and_b32_e32 v24, 0xffff0000, v24
	v_lshlrev_b32_e32 v39, 16, v25
	v_and_b32_e32 v25, 0xffff0000, v25
	s_waitcnt lgkmcnt(1)
	v_mul_f32_e32 v21, v26, v21
	v_mul_f32_e32 v22, v27, v22
	v_mul_f32_e32 v26, v28, v37
	v_mul_f32_e32 v23, v29, v23
	s_waitcnt lgkmcnt(0)
	v_mul_f32_e32 v27, v30, v38
	v_mul_f32_e32 v24, v31, v24
	v_mul_f32_e32 v28, v32, v39
	v_mul_f32_e32 v25, v33, v25
	s_waitcnt vmcnt(0)
	v_mul_f32_e32 v22, v35, v22
	v_mul_f32_e32 v26, v35, v26
	v_mul_f32_e32 v23, v35, v23
	v_mul_f32_e32 v27, v35, v27
	v_mul_f32_e32 v24, v35, v24
	v_mul_f32_e32 v28, v35, v28
	v_mul_f32_e32 v25, v35, v25
	v_mul_f32_e32 v21, v35, v21
	v_cvt_pk_bf16_f32 v22, v21, v22
	v_cvt_pk_bf16_f32 v23, v26, v23
	v_cvt_pk_bf16_f32 v24, v27, v24
	v_cvt_pk_bf16_f32 v25, v28, v25
	global_load_dwordx4 v[26:29], v[18:19], off offset:16
	v_mul_lo_u32 v21, v34, s4
	v_add3_u32 v34, 0, v21, v16
	ds_write_b128 v34, v[22:25] offset:1024
	ds_read_b128 v[22:25], v36 offset:32
	ds_read_b128 v[30:33], v36 offset:48
	s_waitcnt vmcnt(0)
	v_lshlrev_b32_e32 v16, 16, v26
	v_and_b32_e32 v21, 0xffff0000, v26
	v_lshlrev_b32_e32 v26, 16, v27
	v_and_b32_e32 v27, 0xffff0000, v27
	v_lshlrev_b32_e32 v37, 16, v28
	v_and_b32_e32 v28, 0xffff0000, v28
	v_lshlrev_b32_e32 v38, 16, v29
	v_and_b32_e32 v29, 0xffff0000, v29
	s_waitcnt lgkmcnt(1)
	v_mul_f32_e32 v16, v22, v16
	v_mul_f32_e32 v21, v23, v21
	v_mul_f32_e32 v22, v24, v26
	v_mul_f32_e32 v23, v25, v27
	s_waitcnt lgkmcnt(0)
	v_mul_f32_e32 v24, v30, v37
	v_mul_f32_e32 v25, v31, v28
	v_mul_f32_e32 v26, v32, v38
	v_mul_f32_e32 v27, v33, v29
	v_mul_f32_e32 v28, v35, v22
	v_mul_f32_e32 v23, v35, v23
	v_mul_f32_e32 v24, v35, v24
	v_mul_f32_e32 v25, v35, v25
	v_mul_f32_e32 v26, v35, v26
	v_mul_f32_e32 v27, v35, v27
	v_mul_f32_e32 v16, v35, v16
	v_mul_f32_e32 v21, v35, v21
	v_cvt_pk_bf16_f32 v22, v16, v21
	v_cvt_pk_bf16_f32 v23, v28, v23
	v_cvt_pk_bf16_f32 v24, v24, v25
	v_cvt_pk_bf16_f32 v25, v26, v27
	global_load_dwordx4 v[26:29], v[18:19], off offset:32
	ds_write_b128 v34, v[22:25] offset:1040
	ds_read_b128 v[22:25], v36 offset:64
	ds_read_b128 v[30:33], v36 offset:80
	s_waitcnt vmcnt(0)
	v_lshlrev_b32_e32 v16, 16, v26
	v_and_b32_e32 v21, 0xffff0000, v26
	v_lshlrev_b32_e32 v26, 16, v27
	v_and_b32_e32 v27, 0xffff0000, v27
	v_lshlrev_b32_e32 v37, 16, v28
	v_and_b32_e32 v28, 0xffff0000, v28
	v_lshlrev_b32_e32 v38, 16, v29
	v_and_b32_e32 v29, 0xffff0000, v29
	s_waitcnt lgkmcnt(1)
	v_mul_f32_e32 v16, v22, v16
	v_mul_f32_e32 v21, v23, v21
	v_mul_f32_e32 v22, v24, v26
	v_mul_f32_e32 v23, v25, v27
	s_waitcnt lgkmcnt(0)
	v_mul_f32_e32 v24, v30, v37
	v_mul_f32_e32 v25, v31, v28
	v_mul_f32_e32 v26, v32, v38
	v_mul_f32_e32 v27, v33, v29
	v_mul_f32_e32 v28, v35, v22
	v_mul_f32_e32 v23, v35, v23
	v_mul_f32_e32 v24, v35, v24
	v_mul_f32_e32 v25, v35, v25
	v_mul_f32_e32 v26, v35, v26
	v_mul_f32_e32 v27, v35, v27
	v_mul_f32_e32 v16, v35, v16
	v_mul_f32_e32 v21, v35, v21
	v_cvt_pk_bf16_f32 v22, v16, v21
	v_cvt_pk_bf16_f32 v23, v28, v23
	v_cvt_pk_bf16_f32 v24, v24, v25
	v_cvt_pk_bf16_f32 v25, v26, v27
	global_load_dwordx4 v[26:29], v[18:19], off offset:48
	ds_write_b128 v34, v[22:25] offset:1056
	ds_read_b128 v[22:25], v36 offset:96
	ds_read_b128 v[30:33], v36 offset:112
	s_waitcnt vmcnt(0)
	v_lshlrev_b32_e32 v16, 16, v26
	v_and_b32_e32 v21, 0xffff0000, v26
	v_lshlrev_b32_e32 v26, 16, v27
	v_and_b32_e32 v27, 0xffff0000, v27
	v_lshlrev_b32_e32 v37, 16, v28
	v_and_b32_e32 v28, 0xffff0000, v28
	v_lshlrev_b32_e32 v38, 16, v29
	v_and_b32_e32 v29, 0xffff0000, v29
	s_waitcnt lgkmcnt(1)
	v_mul_f32_e32 v16, v22, v16
	v_mul_f32_e32 v21, v23, v21
	v_mul_f32_e32 v22, v24, v26
	v_mul_f32_e32 v23, v25, v27
	s_waitcnt lgkmcnt(0)
	v_mul_f32_e32 v24, v30, v37
	v_mul_f32_e32 v25, v31, v28
	v_mul_f32_e32 v26, v32, v38
	v_mul_f32_e32 v27, v33, v29
	v_mul_f32_e32 v28, v35, v22
	v_mul_f32_e32 v23, v35, v23
	v_mul_f32_e32 v24, v35, v24
	v_mul_f32_e32 v25, v35, v25
	v_mul_f32_e32 v26, v35, v26
	v_mul_f32_e32 v27, v35, v27
	v_mul_f32_e32 v16, v35, v16
	v_mul_f32_e32 v21, v35, v21
	v_cvt_pk_bf16_f32 v22, v16, v21
	v_cvt_pk_bf16_f32 v23, v28, v23
	v_cvt_pk_bf16_f32 v24, v24, v25
	v_cvt_pk_bf16_f32 v25, v26, v27
	global_load_dwordx4 v[26:29], v[18:19], off offset:64
	ds_write_b128 v34, v[22:25] offset:1072
	ds_read_b128 v[22:25], v36 offset:128
	ds_read_b128 v[30:33], v36 offset:144
	s_waitcnt vmcnt(0)
; __device__ __forceinline__ void gmlp_item(PARAMS_T& p, int l, int b, int pos0, int tokrow0) {
;     ...
;   {
;     const int dim = tid >> 1, half = tid & 1;
;     const float gd = p.gm_v_g[l * 256 + dim];
;     const unsigned short* src = (const unsigned short*)(p.ws + OFF_VT) + ((size_t)b * 256 + dim) * PTOK + pos0 + half * 64;
; #pragma unroll
;     for (int i = 0; i < 8; ++i) {
;       u32x4 w = *reinterpret_cast<const u32x4*>(src + i * 8);
;       const int t0 = half * 64 + i * 8;
;       float f0 = __uint_as_float(w[0] << 16) * rs[t0 + 0] * gd, f1 = __uint_as_float(w[0] & 0xffff0000u) * rs[t0 + 1] * gd;
;       float f2 = __uint_as_float(w[1] << 16) * rs[t0 + 2] * gd, f3 = __uint_as_float(w[1] & 0xffff0000u) * rs[t0 + 3] * gd;
;       float f4 = __uint_as_float(w[2] << 16) * rs[t0 + 4] * gd, f5 = __uint_as_float(w[2] & 0xffff0000u) * rs[t0 + 5] * gd;
;       float f6 = __uint_as_float(w[3] << 16) * rs[t0 + 6] * gd, f7 = __uint_as_float(w[3] & 0xffff0000u) * rs[t0 + 7] * gd;
;       u32x4 o = {cvtpk(f0, f1), cvtpk(f2, f3), cvtpk(f4, f5), cvtpk(f6, f7)};
;       *reinterpret_cast<u32x4*>(Vn + dim * 136 + t0) = o;
;     }
;   }
;   __syncthreads();
	v_lshlrev_b32_e32 v16, 16, v26
	v_and_b32_e32 v21, 0xffff0000, v26
	v_lshlrev_b32_e32 v26, 16, v27
	v_and_b32_e32 v27, 0xffff0000, v27
	v_lshlrev_b32_e32 v37, 16, v28
	v_and_b32_e32 v28, 0xffff0000, v28
	v_lshlrev_b32_e32 v38, 16, v29
	v_and_b32_e32 v29, 0xffff0000, v29
	s_waitcnt lgkmcnt(1)
	v_mul_f32_e32 v16, v22, v16
	v_mul_f32_e32 v21, v23, v21
	v_mul_f32_e32 v22, v24, v26
	v_mul_f32_e32 v23, v25, v27
	s_waitcnt lgkmcnt(0)
	v_mul_f32_e32 v24, v30, v37
	v_mul_f32_e32 v25, v31, v28
	v_mul_f32_e32 v26, v32, v38
	v_mul_f32_e32 v27, v33, v29
	v_mul_f32_e32 v28, v35, v22
	v_mul_f32_e32 v23, v35, v23
	v_mul_f32_e32 v24, v35, v24
	v_mul_f32_e32 v25, v35, v25
	v_mul_f32_e32 v26, v35, v26
	v_mul_f32_e32 v27, v35, v27
	v_mul_f32_e32 v16, v35, v16
	v_mul_f32_e32 v21, v35, v21
	v_cvt_pk_bf16_f32 v22, v16, v21
	v_cvt_pk_bf16_f32 v23, v28, v23
	v_cvt_pk_bf16_f32 v24, v24, v25
	v_cvt_pk_bf16_f32 v25, v26, v27
	global_load_dwordx4 v[26:29], v[18:19], off offset:80
	ds_write_b128 v34, v[22:25] offset:1088
	ds_read_b128 v[22:25], v36 offset:160
	ds_read_b128 v[30:33], v36 offset:176
	s_waitcnt vmcnt(0)
	v_lshlrev_b32_e32 v16, 16, v26
	v_and_b32_e32 v21, 0xffff0000, v26
	v_lshlrev_b32_e32 v26, 16, v27
	v_and_b32_e32 v27, 0xffff0000, v27
	v_lshlrev_b32_e32 v37, 16, v28
	v_and_b32_e32 v28, 0xffff0000, v28
	v_lshlrev_b32_e32 v38, 16, v29
	v_and_b32_e32 v29, 0xffff0000, v29
	s_waitcnt lgkmcnt(1)
	v_mul_f32_e32 v16, v22, v16
	v_mul_f32_e32 v21, v23, v21
	v_mul_f32_e32 v22, v24, v26
	v_mul_f32_e32 v23, v25, v27
	s_waitcnt lgkmcnt(0)
	v_mul_f32_e32 v24, v30, v37
	v_mul_f32_e32 v25, v31, v28
	v_mul_f32_e32 v26, v32, v38
	v_mul_f32_e32 v27, v33, v29
	v_mul_f32_e32 v28, v35, v22
	v_mul_f32_e32 v23, v35, v23
	v_mul_f32_e32 v24, v35, v24
	v_mul_f32_e32 v25, v35, v25
	v_mul_f32_e32 v26, v35, v26
	v_mul_f32_e32 v27, v35, v27
	v_mul_f32_e32 v16, v35, v16
	v_mul_f32_e32 v21, v35, v21
	v_cvt_pk_bf16_f32 v22, v16, v21
	v_cvt_pk_bf16_f32 v23, v28, v23
	v_cvt_pk_bf16_f32 v24, v24, v25
	v_cvt_pk_bf16_f32 v25, v26, v27
	global_load_dwordx4 v[26:29], v[18:19], off offset:96
	ds_write_b128 v34, v[22:25] offset:1104
	ds_read_b128 v[22:25], v36 offset:192
	ds_read_b128 v[30:33], v36 offset:208
	s_waitcnt vmcnt(0)
	v_lshlrev_b32_e32 v16, 16, v26
	v_and_b32_e32 v21, 0xffff0000, v26
	v_lshlrev_b32_e32 v26, 16, v27
	v_and_b32_e32 v27, 0xffff0000, v27
	v_lshlrev_b32_e32 v37, 16, v28
	v_and_b32_e32 v28, 0xffff0000, v28
	v_lshlrev_b32_e32 v38, 16, v29
	v_and_b32_e32 v29, 0xffff0000, v29
	s_waitcnt lgkmcnt(1)
	v_mul_f32_e32 v16, v22, v16
	v_mul_f32_e32 v21, v23, v21
	v_mul_f32_e32 v22, v24, v26
	v_mul_f32_e32 v23, v25, v27
	s_waitcnt lgkmcnt(0)
	v_mul_f32_e32 v24, v30, v37
	v_mul_f32_e32 v25, v31, v28
	v_mul_f32_e32 v26, v32, v38
	v_mul_f32_e32 v27, v33, v29
	v_mul_f32_e32 v28, v35, v22
	v_mul_f32_e32 v23, v35, v23
	v_mul_f32_e32 v24, v35, v24
	v_mul_f32_e32 v25, v35, v25
	v_mul_f32_e32 v26, v35, v26
	v_mul_f32_e32 v27, v35, v27
	v_mul_f32_e32 v16, v35, v16
	v_mul_f32_e32 v21, v35, v21
	v_cvt_pk_bf16_f32 v22, v16, v21
	v_cvt_pk_bf16_f32 v23, v28, v23
	v_cvt_pk_bf16_f32 v24, v24, v25
	v_cvt_pk_bf16_f32 v25, v26, v27
	global_load_dwordx4 v[26:29], v[18:19], off offset:112
	v_ashrrev_i32_e32 v31, 7, v20
	v_add_u32_e32 v70, 4, v31
	v_and_b32_e32 v30, 31, v20
	v_ashrrev_i32_e32 v71, 31, v70
	v_lshlrev_b32_e32 v16, 8, v30
	v_lshlrev_b64 v[18:19], 15, v[70:71]
	v_lshl_or_b32 v78, v76, 14, v16
	v_lshl_add_u64 v[18:19], s[8:9], 0, v[18:19]
	v_lshlrev_b32_e32 v16, 4, v73
	ds_write_b128 v34, v[22:25] offset:1120
	v_lshl_add_u64 v[80:81], v[18:19], 0, v[16:17]
	ds_read_b128 v[18:21], v36 offset:224
	ds_read_b128 v[22:25], v36 offset:240
	v_lshl_add_u64 v[74:75], v[80:81], 0, v[78:79]
	v_lshl_or_b32 v72, v31, 6, v30
	v_lshlrev_b64 v[70:71], 9, v[70:71]
	s_waitcnt vmcnt(0)
	v_lshlrev_b32_e32 v32, 16, v26
	v_and_b32_e32 v26, 0xffff0000, v26
	v_lshlrev_b32_e32 v33, 16, v27
	v_and_b32_e32 v27, 0xffff0000, v27
	v_lshlrev_b32_e32 v36, 16, v28
	v_and_b32_e32 v28, 0xffff0000, v28
	v_lshlrev_b32_e32 v37, 16, v29
	v_and_b32_e32 v29, 0xffff0000, v29
	s_waitcnt lgkmcnt(1)
	v_mul_f32_e32 v18, v18, v32
	v_mul_f32_e32 v19, v19, v26
	v_mul_f32_e32 v20, v20, v33
	v_mul_f32_e32 v21, v21, v27
	s_waitcnt lgkmcnt(0)
	v_mul_f32_e32 v22, v22, v36
	v_mul_f32_e32 v23, v23, v28
	v_mul_f32_e32 v24, v24, v37
	v_mul_f32_e32 v25, v25, v29
	v_mul_f32_e32 v18, v35, v18
	v_mul_f32_e32 v19, v35, v19
	v_mul_f32_e32 v20, v35, v20
	v_mul_f32_e32 v21, v35, v21
	v_mul_f32_e32 v22, v35, v22
	v_mul_f32_e32 v23, v35, v23
	v_mul_f32_e32 v24, v35, v24
	v_mul_f32_e32 v25, v35, v25
	v_cvt_pk_bf16_f32 v18, v18, v19
	v_cvt_pk_bf16_f32 v19, v20, v21
	v_cvt_pk_bf16_f32 v20, v22, v23
	v_cvt_pk_bf16_f32 v21, v24, v25
	ds_write_b128 v34, v[18:21] offset:1136
	s_waitcnt lgkmcnt(0)
	s_barrier
; __device__ __forceinline__ void gmlp_item(PARAMS_T& p, int l, int b, int pos0, int tokrow0) {
;     ...
;   const int g = wid >> 1, th = wid & 1;
;   const bf16* wsb = (const bf16*)(p.ws + OFF_WSBF) + ((size_t)l * 4 + g) * 128 * 128;
;   f32x16 acc[2][2] = {};
; #pragma unroll
;   for (int ks = 0; ks < 8; ++ks) {
;     bf16x8 af[2], bfr[2];
; #pragma unroll
;     for (int tb = 0; tb < 2; ++tb) af[tb] = *reinterpret_cast<const bf16x8*>(wsb + (size_t)(th * 64 + tb * 32 + r32) * 128 + ks * 16 + hi * 8);
; #pragma unroll
;     for (int db = 0; db < 2; ++db) bfr[db] = *reinterpret_cast<const bf16x8*>(Vn + (g * 64 + db * 32 + r32) * 136 + ks * 16 + hi * 8);
; #pragma unroll
;     for (int tb = 0; tb < 2; ++tb)
; #pragma unroll
;       for (int db = 0; db < 2; ++db) acc[tb][db] = __builtin_amdgcn_mfma_f32_32x32x16_bf16(af[tb], bfr[db], acc[tb][db], 0, 0, 0);
;   }
	v_and_b32_e32 v250, 31, v192
	v_bfe_u32 v251, v192, 5, 1
	v_lshrrev_b32_e32 v252, 7, v192
	v_bfe_u32 v253, v192, 6, 1
	v_lshl_or_b32 v254, v252, 6, v250
	v_lshlrev_b32_e32 v172, 1, v254
	v_mul_u32_u24_e32 v254, 0x110, v254
	v_lshl_add_u32 v254, v251, 4, v254
	v_add_u32_e32 v16, 0x400, v254
	v_add_u32_e32 v252, 4, v252
	v_lshl_or_b32 v254, v253, 6, v250
	v_lshlrev_b32_e32 v254, 8, v254
	v_lshl_or_b32 v254, v251, 4, v254
	v_lshl_add_u32 v254, v252, 15, v254
	v_mov_b32_e32 v162, v254
	v_mov_b32_e32 v163, 0
	v_lshl_add_u64 v[162:163], s[8:9], 0, v[162:163]
	v_mov_b32_e32 v164, 0x2000
	v_mov_b32_e32 v165, 0
	v_lshl_add_u64 v[164:165], v[162:163], 0, v[164:165]
	global_load_dwordx4 v[82:85], v[162:163], off
	global_load_dwordx4 v[86:89], v[164:165], off
	global_load_dwordx4 v[90:93], v[162:163], off offset:32
	global_load_dwordx4 v[94:97], v[164:165], off offset:32
	global_load_dwordx4 v[98:101], v[162:163], off offset:64
	global_load_dwordx4 v[102:105], v[164:165], off offset:64
	global_load_dwordx4 v[106:109], v[162:163], off offset:96
	global_load_dwordx4 v[110:113], v[164:165], off offset:96
	global_load_dwordx4 v[114:117], v[162:163], off offset:128
	global_load_dwordx4 v[118:121], v[164:165], off offset:128
	global_load_dwordx4 v[122:125], v[162:163], off offset:160
	global_load_dwordx4 v[126:129], v[164:165], off offset:160
	global_load_dwordx4 v[130:133], v[162:163], off offset:192
	global_load_dwordx4 v[134:137], v[164:165], off offset:192
	global_load_dwordx4 v[138:141], v[162:163], off offset:224
	global_load_dwordx4 v[142:145], v[164:165], off offset:224
	v_lshlrev_b32_e32 v171, 6, v253
	v_lshl_add_u32 v171, v251, 2, v171
	v_lshl_add_u32 v170, v252, 7, v171
	v_lshlrev_b32_e32 v170, 2, v170
	v_add_u32_e32 v171, s3, v171
	v_add_u32_e32 v254, 0, v171
	v_lshl_add_u32 v162, v254, 9, v172
	v_add_u32_e32 v254, 8, v171
	v_lshl_add_u32 v163, v254, 9, v172
	v_add_u32_e32 v254, 16, v171
	v_lshl_add_u32 v164, v254, 9, v172
	v_add_u32_e32 v254, 24, v171
	v_lshl_add_u32 v165, v254, 9, v172
	v_add_u32_e32 v254, 32, v171
	v_lshl_add_u32 v166, v254, 9, v172
	v_add_u32_e32 v254, 40, v171
	v_lshl_add_u32 v167, v254, 9, v172
	v_add_u32_e32 v254, 48, v171
	v_lshl_add_u32 v168, v254, 9, v172
	v_add_u32_e32 v254, 56, v171
	v_lshl_add_u32 v169, v254, 9, v172
	v_mov_b32_e32 v18, 0
	v_mov_b32_e32 v19, 0
	v_mov_b32_e32 v20, 0
	v_mov_b32_e32 v21, 0
	v_mov_b32_e32 v22, 0
	v_mov_b32_e32 v23, 0
	v_mov_b32_e32 v24, 0
	v_mov_b32_e32 v25, 0
	v_mov_b32_e32 v26, 0
	v_mov_b32_e32 v27, 0
	v_mov_b32_e32 v28, 0
	v_mov_b32_e32 v29, 0
	v_mov_b32_e32 v30, 0
	v_mov_b32_e32 v31, 0
	v_mov_b32_e32 v32, 0
	v_mov_b32_e32 v33, 0
	v_mov_b32_e32 v34, 0
	v_mov_b32_e32 v35, 0
	v_mov_b32_e32 v36, 0
	v_mov_b32_e32 v37, 0
	v_mov_b32_e32 v38, 0
	v_mov_b32_e32 v39, 0
	v_mov_b32_e32 v40, 0
	v_mov_b32_e32 v41, 0
	v_mov_b32_e32 v42, 0
	v_mov_b32_e32 v43, 0
	v_mov_b32_e32 v44, 0
	v_mov_b32_e32 v45, 0
	v_mov_b32_e32 v46, 0
	v_mov_b32_e32 v47, 0
	v_mov_b32_e32 v48, 0
	v_mov_b32_e32 v49, 0
	v_mov_b32_e32 v50, 0
	v_mov_b32_e32 v51, 0
	v_mov_b32_e32 v52, 0
	v_mov_b32_e32 v53, 0
	v_mov_b32_e32 v54, 0
	v_mov_b32_e32 v55, 0
	v_mov_b32_e32 v56, 0
	v_mov_b32_e32 v57, 0
	v_mov_b32_e32 v58, 0
	v_mov_b32_e32 v59, 0
	v_mov_b32_e32 v60, 0
	v_mov_b32_e32 v61, 0
	v_mov_b32_e32 v62, 0
	v_mov_b32_e32 v63, 0
	v_mov_b32_e32 v64, 0
	v_mov_b32_e32 v65, 0
	v_mov_b32_e32 v66, 0
	v_mov_b32_e32 v67, 0
	v_mov_b32_e32 v68, 0
	v_mov_b32_e32 v69, 0
	v_mov_b32_e32 v70, 0
	v_mov_b32_e32 v71, 0
	v_mov_b32_e32 v72, 0
	v_mov_b32_e32 v73, 0
	v_mov_b32_e32 v74, 0
	v_mov_b32_e32 v75, 0
	v_mov_b32_e32 v76, 0
	v_mov_b32_e32 v77, 0
	v_mov_b32_e32 v78, 0
	v_mov_b32_e32 v79, 0
	v_mov_b32_e32 v80, 0
	v_mov_b32_e32 v81, 0
	ds_read_b128 v[146:149], v16 offset:0
	ds_read_b128 v[150:153], v16 offset:8704
	ds_read_b128 v[154:157], v16 offset:32
	ds_read_b128 v[158:161], v16 offset:8736
	ds_read_b128 v[234:237], v16 offset:64
	ds_read_b128 v[238:241], v16 offset:8768
	ds_read_b128 v[242:245], v16 offset:96
	ds_read_b128 v[246:249], v16 offset:8800
	s_waitcnt vmcnt(15) lgkmcnt(7)
	v_mfma_f32_32x32x16_bf16 v[18:33], v[82:85], v[146:149], v[18:33]
	s_waitcnt vmcnt(15) lgkmcnt(6)
	v_mfma_f32_32x32x16_bf16 v[34:49], v[82:85], v[150:153], v[34:49]
	s_waitcnt vmcnt(14)
	v_mfma_f32_32x32x16_bf16 v[50:65], v[86:89], v[146:149], v[50:65]
	v_mfma_f32_32x32x16_bf16 v[66:81], v[86:89], v[150:153], v[66:81]
	s_waitcnt vmcnt(13) lgkmcnt(5)
	v_mfma_f32_32x32x16_bf16 v[18:33], v[90:93], v[154:157], v[18:33]
	s_waitcnt vmcnt(13) lgkmcnt(4)
	v_mfma_f32_32x32x16_bf16 v[34:49], v[90:93], v[158:161], v[34:49]
	s_waitcnt vmcnt(12)
	v_mfma_f32_32x32x16_bf16 v[50:65], v[94:97], v[154:157], v[50:65]
	v_mfma_f32_32x32x16_bf16 v[66:81], v[94:97], v[158:161], v[66:81]
	s_waitcnt vmcnt(11) lgkmcnt(3)
	v_mfma_f32_32x32x16_bf16 v[18:33], v[98:101], v[234:237], v[18:33]
	s_waitcnt vmcnt(11) lgkmcnt(2)
	v_mfma_f32_32x32x16_bf16 v[34:49], v[98:101], v[238:241], v[34:49]
	s_waitcnt vmcnt(10)
	v_mfma_f32_32x32x16_bf16 v[50:65], v[102:105], v[234:237], v[50:65]
	v_mfma_f32_32x32x16_bf16 v[66:81], v[102:105], v[238:241], v[66:81]
	s_waitcnt vmcnt(9) lgkmcnt(1)
	v_mfma_f32_32x32x16_bf16 v[18:33], v[106:109], v[242:245], v[18:33]
	s_waitcnt vmcnt(9) lgkmcnt(0)
	v_mfma_f32_32x32x16_bf16 v[34:49], v[106:109], v[246:249], v[34:49]
	s_waitcnt vmcnt(8)
	v_mfma_f32_32x32x16_bf16 v[50:65], v[110:113], v[242:245], v[50:65]
	v_mfma_f32_32x32x16_bf16 v[66:81], v[110:113], v[246:249], v[66:81]
	ds_read_b128 v[146:149], v16 offset:128
	ds_read_b128 v[150:153], v16 offset:8832
	ds_read_b128 v[154:157], v16 offset:160
	ds_read_b128 v[158:161], v16 offset:8864
	ds_read_b128 v[234:237], v16 offset:192
	ds_read_b128 v[238:241], v16 offset:8896
	ds_read_b128 v[242:245], v16 offset:224
	ds_read_b128 v[246:249], v16 offset:8928
	s_waitcnt vmcnt(7) lgkmcnt(7)
; __device__ __forceinline__ unsigned short bf1(float a) { return (unsigned short)(cvtpk(a, 0.f) & 0xffffu); }
; __device__ __forceinline__ int crow(int r, int hi) { return (r & 3) + 8 * (r >> 2) + 4 * hi; }
; __device__ __forceinline__ void gmlp_item(PARAMS_T& p, int l, int b, int pos0, int tokrow0) {
;     ...
; #pragma unroll
;   for (int ks = 0; ks < 8; ++ks) {
;     bf16x8 af[2], bfr[2];
; #pragma unroll
;     for (int tb = 0; tb < 2; ++tb) af[tb] = *reinterpret_cast<const bf16x8*>(wsb + (size_t)(th * 64 + tb * 32 + r32) * 128 + ks * 16 + hi * 8);
; #pragma unroll
;     for (int db = 0; db < 2; ++db) bfr[db] = *reinterpret_cast<const bf16x8*>(Vn + (g * 64 + db * 32 + r32) * 136 + ks * 16 + hi * 8);
; #pragma unroll
;     for (int tb = 0; tb < 2; ++tb)
; #pragma unroll
;       for (int db = 0; db < 2; ++db) acc[tb][db] = __builtin_amdgcn_mfma_f32_32x32x16_bf16(af[tb], bfr[db], acc[tb][db], 0, 0, 0);
;   }
;   const float* bs = p.gm_bs + ((size_t)l * 4 + g) * 128;
;   const unsigned short* u = (const unsigned short*)(p.ws + OFF_U);
;   unsigned short* outp = (unsigned short*)(p.ws + OFF_ACTA);
; #pragma unroll
;   for (int tb = 0; tb < 2; ++tb)
; #pragma unroll
;     for (int r = 0; r < 16; ++r) {
;       const int t = th * 64 + tb * 32 + crow(r, hi);
;       const float bt = bs[t];
; #pragma unroll
;       for (int db = 0; db < 2; ++db) {
;         const int d = g * 64 + db * 32 + r32;
;         const float uv = __uint_as_float(((unsigned)u[(size_t)(tokrow0 + t) * 256 + d]) << 16);
;         outp[(size_t)(tokrow0 + t) * 1024 + 256 + d] = bf1(uv * (acc[tb][db][r] + bt));
;       }
;     }
	v_mfma_f32_32x32x16_bf16 v[18:33], v[114:117], v[146:149], v[18:33]
	s_waitcnt vmcnt(7) lgkmcnt(6)
	v_mfma_f32_32x32x16_bf16 v[34:49], v[114:117], v[150:153], v[34:49]
	s_waitcnt vmcnt(6)
	v_mfma_f32_32x32x16_bf16 v[50:65], v[118:121], v[146:149], v[50:65]
	v_mfma_f32_32x32x16_bf16 v[66:81], v[118:121], v[150:153], v[66:81]
	s_waitcnt vmcnt(5) lgkmcnt(5)
	v_mfma_f32_32x32x16_bf16 v[18:33], v[122:125], v[154:157], v[18:33]
	s_waitcnt vmcnt(5) lgkmcnt(4)
	v_mfma_f32_32x32x16_bf16 v[34:49], v[122:125], v[158:161], v[34:49]
	s_waitcnt vmcnt(4)
	v_mfma_f32_32x32x16_bf16 v[50:65], v[126:129], v[154:157], v[50:65]
	v_mfma_f32_32x32x16_bf16 v[66:81], v[126:129], v[158:161], v[66:81]
	s_waitcnt vmcnt(3) lgkmcnt(3)
	v_mfma_f32_32x32x16_bf16 v[18:33], v[130:133], v[234:237], v[18:33]
	s_waitcnt vmcnt(3) lgkmcnt(2)
	v_mfma_f32_32x32x16_bf16 v[34:49], v[130:133], v[238:241], v[34:49]
	s_waitcnt vmcnt(2)
	v_mfma_f32_32x32x16_bf16 v[50:65], v[134:137], v[234:237], v[50:65]
	v_mfma_f32_32x32x16_bf16 v[66:81], v[134:137], v[238:241], v[66:81]
	s_waitcnt vmcnt(1) lgkmcnt(1)
	v_mfma_f32_32x32x16_bf16 v[18:33], v[138:141], v[242:245], v[18:33]
	s_waitcnt vmcnt(1) lgkmcnt(0)
	v_mfma_f32_32x32x16_bf16 v[34:49], v[138:141], v[246:249], v[34:49]
	s_waitcnt vmcnt(0)
	v_mfma_f32_32x32x16_bf16 v[50:65], v[142:145], v[242:245], v[50:65]
	v_mfma_f32_32x32x16_bf16 v[66:81], v[142:145], v[246:249], v[66:81]
	global_load_dwordx4 v[146:149], v170, s[6:7]
	global_load_ushort v82, v162, s[94:95]
	global_load_ushort v83, v162, s[94:95] offset:64
	global_load_ushort v84, v162, s[94:95] offset:512
	global_load_ushort v85, v162, s[94:95] offset:576
	global_load_ushort v86, v162, s[94:95] offset:1024
	global_load_ushort v87, v162, s[94:95] offset:1088
	global_load_ushort v88, v162, s[94:95] offset:1536
	global_load_ushort v89, v162, s[94:95] offset:1600
	global_load_dwordx4 v[150:153], v170, s[6:7] offset:32
	global_load_ushort v90, v163, s[94:95]
	global_load_ushort v91, v163, s[94:95] offset:64
	global_load_ushort v92, v163, s[94:95] offset:512
	global_load_ushort v93, v163, s[94:95] offset:576
	global_load_ushort v94, v163, s[94:95] offset:1024
	global_load_ushort v95, v163, s[94:95] offset:1088
	global_load_ushort v96, v163, s[94:95] offset:1536
	global_load_ushort v97, v163, s[94:95] offset:1600
	global_load_dwordx4 v[154:157], v170, s[6:7] offset:64
	global_load_ushort v98, v164, s[94:95]
	global_load_ushort v99, v164, s[94:95] offset:64
	global_load_ushort v100, v164, s[94:95] offset:512
	global_load_ushort v101, v164, s[94:95] offset:576
	global_load_ushort v102, v164, s[94:95] offset:1024
	global_load_ushort v103, v164, s[94:95] offset:1088
	global_load_ushort v104, v164, s[94:95] offset:1536
	global_load_ushort v105, v164, s[94:95] offset:1600
	global_load_dwordx4 v[158:161], v170, s[6:7] offset:96
	global_load_ushort v106, v165, s[94:95]
	global_load_ushort v107, v165, s[94:95] offset:64
	global_load_ushort v108, v165, s[94:95] offset:512
	global_load_ushort v109, v165, s[94:95] offset:576
	global_load_ushort v110, v165, s[94:95] offset:1024
	global_load_ushort v111, v165, s[94:95] offset:1088
	global_load_ushort v112, v165, s[94:95] offset:1536
	global_load_ushort v113, v165, s[94:95] offset:1600
	global_load_dwordx4 v[234:237], v170, s[6:7] offset:128
	global_load_ushort v114, v166, s[94:95]
	global_load_ushort v115, v166, s[94:95] offset:64
	global_load_ushort v116, v166, s[94:95] offset:512
	global_load_ushort v117, v166, s[94:95] offset:576
	global_load_ushort v118, v166, s[94:95] offset:1024
	global_load_ushort v119, v166, s[94:95] offset:1088
	global_load_ushort v120, v166, s[94:95] offset:1536
	global_load_ushort v121, v166, s[94:95] offset:1600
	global_load_dwordx4 v[238:241], v170, s[6:7] offset:160
	global_load_ushort v122, v167, s[94:95]
	global_load_ushort v123, v167, s[94:95] offset:64
	global_load_ushort v124, v167, s[94:95] offset:512
	global_load_ushort v125, v167, s[94:95] offset:576
	global_load_ushort v126, v167, s[94:95] offset:1024
	global_load_ushort v127, v167, s[94:95] offset:1088
	global_load_ushort v128, v167, s[94:95] offset:1536
	global_load_ushort v129, v167, s[94:95] offset:1600
	global_load_dwordx4 v[242:245], v170, s[6:7] offset:192
	global_load_ushort v130, v168, s[94:95]
	global_load_ushort v131, v168, s[94:95] offset:64
	global_load_ushort v132, v168, s[94:95] offset:512
	global_load_ushort v133, v168, s[94:95] offset:576
	global_load_ushort v134, v168, s[94:95] offset:1024
	global_load_ushort v135, v168, s[94:95] offset:1088
	global_load_ushort v136, v168, s[94:95] offset:1536
	global_load_ushort v137, v168, s[94:95] offset:1600
	global_load_dwordx4 v[246:249], v170, s[6:7] offset:224
	global_load_ushort v138, v169, s[94:95]
	global_load_ushort v139, v169, s[94:95] offset:64
	global_load_ushort v140, v169, s[94:95] offset:512
	global_load_ushort v141, v169, s[94:95] offset:576
	global_load_ushort v142, v169, s[94:95] offset:1024
	global_load_ushort v143, v169, s[94:95] offset:1088
	global_load_ushort v144, v169, s[94:95] offset:1536
	global_load_ushort v145, v169, s[94:95] offset:1600
	s_waitcnt vmcnt(63)
	v_add_f32_e32 v250, v18, v146
	v_lshlrev_b32_e32 v82, 16, v82
	v_mul_f32_e32 v82, v250, v82
	v_cvt_pk_bf16_f32 v82, v82, v17
	v_add_f32_e32 v251, v34, v146
	v_lshlrev_b32_e32 v83, 16, v83
	v_mul_f32_e32 v83, v251, v83
	v_cvt_pk_bf16_f32 v83, v83, v17
	s_waitcnt vmcnt(63)
	v_add_f32_e32 v250, v19, v147
	v_lshlrev_b32_e32 v84, 16, v84
	v_mul_f32_e32 v84, v250, v84
	v_cvt_pk_bf16_f32 v84, v84, v17
	v_add_f32_e32 v251, v35, v147
	v_lshlrev_b32_e32 v85, 16, v85
	v_mul_f32_e32 v85, v251, v85
	v_cvt_pk_bf16_f32 v85, v85, v17
	s_waitcnt vmcnt(63)
; __device__ __forceinline__ unsigned short bf1(float a) { return (unsigned short)(cvtpk(a, 0.f) & 0xffffu); }
; __device__ __forceinline__ int crow(int r, int hi) { return (r & 3) + 8 * (r >> 2) + 4 * hi; }
; __device__ __forceinline__ void gmlp_item(PARAMS_T& p, int l, int b, int pos0, int tokrow0) {
;     ...
; #pragma unroll
;   for (int tb = 0; tb < 2; ++tb)
; #pragma unroll
;     for (int r = 0; r < 16; ++r) {
;       const int t = th * 64 + tb * 32 + crow(r, hi);
;       const float bt = bs[t];
; #pragma unroll
;       for (int db = 0; db < 2; ++db) {
;         const int d = g * 64 + db * 32 + r32;
;         const float uv = __uint_as_float(((unsigned)u[(size_t)(tokrow0 + t) * 256 + d]) << 16);
;         outp[(size_t)(tokrow0 + t) * 1024 + 256 + d] = bf1(uv * (acc[tb][db][r] + bt));
;       }
;     }
	v_add_f32_e32 v250, v20, v148
	v_lshlrev_b32_e32 v86, 16, v86
	v_mul_f32_e32 v86, v250, v86
	v_cvt_pk_bf16_f32 v86, v86, v17
	v_add_f32_e32 v251, v36, v148
	v_lshlrev_b32_e32 v87, 16, v87
	v_mul_f32_e32 v87, v251, v87
	v_cvt_pk_bf16_f32 v87, v87, v17
	s_waitcnt vmcnt(63)
	v_add_f32_e32 v250, v21, v149
	v_lshlrev_b32_e32 v88, 16, v88
	v_mul_f32_e32 v88, v250, v88
	v_cvt_pk_bf16_f32 v88, v88, v17
	v_add_f32_e32 v251, v37, v149
	v_lshlrev_b32_e32 v89, 16, v89
	v_mul_f32_e32 v89, v251, v89
	v_cvt_pk_bf16_f32 v89, v89, v17
	s_waitcnt vmcnt(60)
	v_add_f32_e32 v250, v22, v150
	v_lshlrev_b32_e32 v90, 16, v90
	v_mul_f32_e32 v90, v250, v90
	v_cvt_pk_bf16_f32 v90, v90, v17
	v_add_f32_e32 v251, v38, v150
	v_lshlrev_b32_e32 v91, 16, v91
	v_mul_f32_e32 v91, v251, v91
	v_cvt_pk_bf16_f32 v91, v91, v17
	s_waitcnt vmcnt(58)
	v_add_f32_e32 v250, v23, v151
	v_lshlrev_b32_e32 v92, 16, v92
	v_mul_f32_e32 v92, v250, v92
	v_cvt_pk_bf16_f32 v92, v92, v17
	v_add_f32_e32 v251, v39, v151
	v_lshlrev_b32_e32 v93, 16, v93
	v_mul_f32_e32 v93, v251, v93
	v_cvt_pk_bf16_f32 v93, v93, v17
	s_waitcnt vmcnt(56)
	v_add_f32_e32 v250, v24, v152
	v_lshlrev_b32_e32 v94, 16, v94
	v_mul_f32_e32 v94, v250, v94
	v_cvt_pk_bf16_f32 v94, v94, v17
	v_add_f32_e32 v251, v40, v152
	v_lshlrev_b32_e32 v95, 16, v95
	v_mul_f32_e32 v95, v251, v95
	v_cvt_pk_bf16_f32 v95, v95, v17
	s_waitcnt vmcnt(54)
	v_add_f32_e32 v250, v25, v153
	v_lshlrev_b32_e32 v96, 16, v96
	v_mul_f32_e32 v96, v250, v96
	v_cvt_pk_bf16_f32 v96, v96, v17
	v_add_f32_e32 v251, v41, v153
	v_lshlrev_b32_e32 v97, 16, v97
	v_mul_f32_e32 v97, v251, v97
	v_cvt_pk_bf16_f32 v97, v97, v17
	s_waitcnt vmcnt(51)
	v_add_f32_e32 v250, v26, v154
	v_lshlrev_b32_e32 v98, 16, v98
	v_mul_f32_e32 v98, v250, v98
	v_cvt_pk_bf16_f32 v98, v98, v17
	v_add_f32_e32 v251, v42, v154
	v_lshlrev_b32_e32 v99, 16, v99
	v_mul_f32_e32 v99, v251, v99
	v_cvt_pk_bf16_f32 v99, v99, v17
	s_waitcnt vmcnt(49)
	v_add_f32_e32 v250, v27, v155
	v_lshlrev_b32_e32 v100, 16, v100
	v_mul_f32_e32 v100, v250, v100
	v_cvt_pk_bf16_f32 v100, v100, v17
	v_add_f32_e32 v251, v43, v155
	v_lshlrev_b32_e32 v101, 16, v101
	v_mul_f32_e32 v101, v251, v101
	v_cvt_pk_bf16_f32 v101, v101, v17
	s_waitcnt vmcnt(47)
	v_add_f32_e32 v250, v28, v156
	v_lshlrev_b32_e32 v102, 16, v102
	v_mul_f32_e32 v102, v250, v102
	v_cvt_pk_bf16_f32 v102, v102, v17
	v_add_f32_e32 v251, v44, v156
	v_lshlrev_b32_e32 v103, 16, v103
	v_mul_f32_e32 v103, v251, v103
	v_cvt_pk_bf16_f32 v103, v103, v17
	s_waitcnt vmcnt(45)
	v_add_f32_e32 v250, v29, v157
	v_lshlrev_b32_e32 v104, 16, v104
	v_mul_f32_e32 v104, v250, v104
	v_cvt_pk_bf16_f32 v104, v104, v17
	v_add_f32_e32 v251, v45, v157
	v_lshlrev_b32_e32 v105, 16, v105
	v_mul_f32_e32 v105, v251, v105
	v_cvt_pk_bf16_f32 v105, v105, v17
	s_waitcnt vmcnt(42)
	v_add_f32_e32 v250, v30, v158
	v_lshlrev_b32_e32 v106, 16, v106
	v_mul_f32_e32 v106, v250, v106
	v_cvt_pk_bf16_f32 v106, v106, v17
	v_add_f32_e32 v251, v46, v158
	v_lshlrev_b32_e32 v107, 16, v107
	v_mul_f32_e32 v107, v251, v107
	v_cvt_pk_bf16_f32 v107, v107, v17
	s_waitcnt vmcnt(40)
	v_add_f32_e32 v250, v31, v159
	v_lshlrev_b32_e32 v108, 16, v108
	v_mul_f32_e32 v108, v250, v108
	v_cvt_pk_bf16_f32 v108, v108, v17
	v_add_f32_e32 v251, v47, v159
	v_lshlrev_b32_e32 v109, 16, v109
	v_mul_f32_e32 v109, v251, v109
	v_cvt_pk_bf16_f32 v109, v109, v17
	s_waitcnt vmcnt(38)
	v_add_f32_e32 v250, v32, v160
	v_lshlrev_b32_e32 v110, 16, v110
	v_mul_f32_e32 v110, v250, v110
	v_cvt_pk_bf16_f32 v110, v110, v17
	v_add_f32_e32 v251, v48, v160
	v_lshlrev_b32_e32 v111, 16, v111
	v_mul_f32_e32 v111, v251, v111
	v_cvt_pk_bf16_f32 v111, v111, v17
	s_waitcnt vmcnt(36)
	v_add_f32_e32 v250, v33, v161
	v_lshlrev_b32_e32 v112, 16, v112
	v_mul_f32_e32 v112, v250, v112
	v_cvt_pk_bf16_f32 v112, v112, v17
	v_add_f32_e32 v251, v49, v161
	v_lshlrev_b32_e32 v113, 16, v113
	v_mul_f32_e32 v113, v251, v113
	v_cvt_pk_bf16_f32 v113, v113, v17
	s_waitcnt vmcnt(33)
	v_add_f32_e32 v250, v50, v234
	v_lshlrev_b32_e32 v114, 16, v114
	v_mul_f32_e32 v114, v250, v114
	v_cvt_pk_bf16_f32 v114, v114, v17
	v_add_f32_e32 v251, v66, v234
	v_lshlrev_b32_e32 v115, 16, v115
	v_mul_f32_e32 v115, v251, v115
	v_cvt_pk_bf16_f32 v115, v115, v17
	s_waitcnt vmcnt(31)
	v_add_f32_e32 v250, v51, v235
	v_lshlrev_b32_e32 v116, 16, v116
	v_mul_f32_e32 v116, v250, v116
	v_cvt_pk_bf16_f32 v116, v116, v17
	v_add_f32_e32 v251, v67, v235
	v_lshlrev_b32_e32 v117, 16, v117
	v_mul_f32_e32 v117, v251, v117
	v_cvt_pk_bf16_f32 v117, v117, v17
	s_waitcnt vmcnt(29)
	v_add_f32_e32 v250, v52, v236
	v_lshlrev_b32_e32 v118, 16, v118
	v_mul_f32_e32 v118, v250, v118
	v_cvt_pk_bf16_f32 v118, v118, v17
	v_add_f32_e32 v251, v68, v236
	v_lshlrev_b32_e32 v119, 16, v119
	v_mul_f32_e32 v119, v251, v119
	v_cvt_pk_bf16_f32 v119, v119, v17
	s_waitcnt vmcnt(27)
	v_add_f32_e32 v250, v53, v237
	v_lshlrev_b32_e32 v120, 16, v120
	v_mul_f32_e32 v120, v250, v120
	v_cvt_pk_bf16_f32 v120, v120, v17
	v_add_f32_e32 v251, v69, v237
	v_lshlrev_b32_e32 v121, 16, v121
	v_mul_f32_e32 v121, v251, v121
	v_cvt_pk_bf16_f32 v121, v121, v17
	s_waitcnt vmcnt(24)
	v_add_f32_e32 v250, v54, v238
	v_lshlrev_b32_e32 v122, 16, v122
	v_mul_f32_e32 v122, v250, v122
	v_cvt_pk_bf16_f32 v122, v122, v17
	v_add_f32_e32 v251, v70, v238
	v_lshlrev_b32_e32 v123, 16, v123
	v_mul_f32_e32 v123, v251, v123
	v_cvt_pk_bf16_f32 v123, v123, v17
	s_waitcnt vmcnt(22)
	v_add_f32_e32 v250, v55, v239
	v_lshlrev_b32_e32 v124, 16, v124
	v_mul_f32_e32 v124, v250, v124
	v_cvt_pk_bf16_f32 v124, v124, v17
	v_add_f32_e32 v251, v71, v239
	v_lshlrev_b32_e32 v125, 16, v125
	v_mul_f32_e32 v125, v251, v125
	v_cvt_pk_bf16_f32 v125, v125, v17
	s_waitcnt vmcnt(20)
; __device__ __forceinline__ unsigned short bf1(float a) { return (unsigned short)(cvtpk(a, 0.f) & 0xffffu); }
; __device__ __forceinline__ int crow(int r, int hi) { return (r & 3) + 8 * (r >> 2) + 4 * hi; }
; __device__ __forceinline__ void gmlp_item(PARAMS_T& p, int l, int b, int pos0, int tokrow0) {
;     ...
; #pragma unroll
;   for (int tb = 0; tb < 2; ++tb)
; #pragma unroll
;     for (int r = 0; r < 16; ++r) {
;       const int t = th * 64 + tb * 32 + crow(r, hi);
;       const float bt = bs[t];
; #pragma unroll
;       for (int db = 0; db < 2; ++db) {
;         const int d = g * 64 + db * 32 + r32;
;         const float uv = __uint_as_float(((unsigned)u[(size_t)(tokrow0 + t) * 256 + d]) << 16);
;         outp[(size_t)(tokrow0 + t) * 1024 + 256 + d] = bf1(uv * (acc[tb][db][r] + bt));
;       }
;     }
	v_add_f32_e32 v250, v56, v240
	v_lshlrev_b32_e32 v126, 16, v126
	v_mul_f32_e32 v126, v250, v126
	v_cvt_pk_bf16_f32 v126, v126, v17
	v_add_f32_e32 v251, v72, v240
	v_lshlrev_b32_e32 v127, 16, v127
	v_mul_f32_e32 v127, v251, v127
	v_cvt_pk_bf16_f32 v127, v127, v17
	s_waitcnt vmcnt(18)
	v_add_f32_e32 v250, v57, v241
	v_lshlrev_b32_e32 v128, 16, v128
	v_mul_f32_e32 v128, v250, v128
	v_cvt_pk_bf16_f32 v128, v128, v17
	v_add_f32_e32 v251, v73, v241
	v_lshlrev_b32_e32 v129, 16, v129
	v_mul_f32_e32 v129, v251, v129
	v_cvt_pk_bf16_f32 v129, v129, v17
	s_waitcnt vmcnt(15)
	v_add_f32_e32 v250, v58, v242
	v_lshlrev_b32_e32 v130, 16, v130
	v_mul_f32_e32 v130, v250, v130
	v_cvt_pk_bf16_f32 v130, v130, v17
	v_add_f32_e32 v251, v74, v242
	v_lshlrev_b32_e32 v131, 16, v131
	v_mul_f32_e32 v131, v251, v131
	v_cvt_pk_bf16_f32 v131, v131, v17
	s_waitcnt vmcnt(13)
	v_add_f32_e32 v250, v59, v243
	v_lshlrev_b32_e32 v132, 16, v132
	v_mul_f32_e32 v132, v250, v132
	v_cvt_pk_bf16_f32 v132, v132, v17
	v_add_f32_e32 v251, v75, v243
	v_lshlrev_b32_e32 v133, 16, v133
	v_mul_f32_e32 v133, v251, v133
	v_cvt_pk_bf16_f32 v133, v133, v17
	s_waitcnt vmcnt(11)
	v_add_f32_e32 v250, v60, v244
	v_lshlrev_b32_e32 v134, 16, v134
	v_mul_f32_e32 v134, v250, v134
	v_cvt_pk_bf16_f32 v134, v134, v17
	v_add_f32_e32 v251, v76, v244
	v_lshlrev_b32_e32 v135, 16, v135
	v_mul_f32_e32 v135, v251, v135
	v_cvt_pk_bf16_f32 v135, v135, v17
	s_waitcnt vmcnt(9)
	v_add_f32_e32 v250, v61, v245
	v_lshlrev_b32_e32 v136, 16, v136
	v_mul_f32_e32 v136, v250, v136
	v_cvt_pk_bf16_f32 v136, v136, v17
	v_add_f32_e32 v251, v77, v245
	v_lshlrev_b32_e32 v137, 16, v137
	v_mul_f32_e32 v137, v251, v137
	v_cvt_pk_bf16_f32 v137, v137, v17
	s_waitcnt vmcnt(6)
	v_add_f32_e32 v250, v62, v246
	v_lshlrev_b32_e32 v138, 16, v138
	v_mul_f32_e32 v138, v250, v138
	v_cvt_pk_bf16_f32 v138, v138, v17
	v_add_f32_e32 v251, v78, v246
	v_lshlrev_b32_e32 v139, 16, v139
	v_mul_f32_e32 v139, v251, v139
	v_cvt_pk_bf16_f32 v139, v139, v17
	s_waitcnt vmcnt(4)
	v_add_f32_e32 v250, v63, v247
	v_lshlrev_b32_e32 v140, 16, v140
	v_mul_f32_e32 v140, v250, v140
	v_cvt_pk_bf16_f32 v140, v140, v17
	v_add_f32_e32 v251, v79, v247
	v_lshlrev_b32_e32 v141, 16, v141
	v_mul_f32_e32 v141, v251, v141
	v_cvt_pk_bf16_f32 v141, v141, v17
	s_waitcnt vmcnt(2)
	v_add_f32_e32 v250, v64, v248
	v_lshlrev_b32_e32 v142, 16, v142
	v_mul_f32_e32 v142, v250, v142
	v_cvt_pk_bf16_f32 v142, v142, v17
	v_add_f32_e32 v251, v80, v248
	v_lshlrev_b32_e32 v143, 16, v143
	v_mul_f32_e32 v143, v251, v143
	v_cvt_pk_bf16_f32 v143, v143, v17
	s_waitcnt vmcnt(0)
; __device__ __forceinline__ unsigned short bf1(float a) { return (unsigned short)(cvtpk(a, 0.f) & 0xffffu); }
; __device__ __forceinline__ int crow(int r, int hi) { return (r & 3) + 8 * (r >> 2) + 4 * hi; }
; __device__ __forceinline__ void gmlp_item(PARAMS_T& p, int l, int b, int pos0, int tokrow0) {
;     ...
; #pragma unroll
;   for (int tb = 0; tb < 2; ++tb)
; #pragma unroll
;     for (int r = 0; r < 16; ++r) {
;       const int t = th * 64 + tb * 32 + crow(r, hi);
;       const float bt = bs[t];
; #pragma unroll
;       for (int db = 0; db < 2; ++db) {
;         const int d = g * 64 + db * 32 + r32;
;         const float uv = __uint_as_float(((unsigned)u[(size_t)(tokrow0 + t) * 256 + d]) << 16);
;         outp[(size_t)(tokrow0 + t) * 1024 + 256 + d] = bf1(uv * (acc[tb][db][r] + bt));
;       }
;     }
	v_add_f32_e32 v250, v65, v249
	v_lshlrev_b32_e32 v144, 16, v144
	v_mul_f32_e32 v144, v250, v144
	v_cvt_pk_bf16_f32 v144, v144, v17
	v_add_f32_e32 v251, v81, v249
	v_lshlrev_b32_e32 v145, 16, v145
	v_mul_f32_e32 v145, v251, v145
	v_cvt_pk_bf16_f32 v145, v145, v17
	v_add_u32_e32 v254, 0, v171
	v_lshl_add_u32 v146, v254, 11, v172
	v_add_u32_e32 v254, 2, v171
	v_lshl_add_u32 v147, v254, 11, v172
	v_add_u32_e32 v254, 8, v171
	v_lshl_add_u32 v148, v254, 11, v172
	v_add_u32_e32 v254, 10, v171
	v_lshl_add_u32 v149, v254, 11, v172
	v_add_u32_e32 v254, 16, v171
	v_lshl_add_u32 v150, v254, 11, v172
	v_add_u32_e32 v254, 18, v171
	v_lshl_add_u32 v151, v254, 11, v172
	v_add_u32_e32 v254, 24, v171
	v_lshl_add_u32 v152, v254, 11, v172
	v_add_u32_e32 v254, 26, v171
	v_lshl_add_u32 v153, v254, 11, v172
	v_add_u32_e32 v254, 32, v171
	v_lshl_add_u32 v154, v254, 11, v172
	v_add_u32_e32 v254, 34, v171
	v_lshl_add_u32 v155, v254, 11, v172
	v_add_u32_e32 v254, 40, v171
	v_lshl_add_u32 v156, v254, 11, v172
	v_add_u32_e32 v254, 42, v171
	v_lshl_add_u32 v157, v254, 11, v172
	v_add_u32_e32 v254, 48, v171
	v_lshl_add_u32 v158, v254, 11, v172
	v_add_u32_e32 v254, 50, v171
	v_lshl_add_u32 v159, v254, 11, v172
	v_add_u32_e32 v254, 56, v171
	v_lshl_add_u32 v160, v254, 11, v172
	v_add_u32_e32 v254, 58, v171
	v_lshl_add_u32 v161, v254, 11, v172
	global_store_short v146, v82, s[96:97]
	global_store_short v146, v83, s[96:97] offset:64
	global_store_short v146, v84, s[96:97] offset:2048
	global_store_short v146, v85, s[96:97] offset:2112
	global_store_short v147, v86, s[96:97]
	global_store_short v147, v87, s[96:97] offset:64
	global_store_short v147, v88, s[96:97] offset:2048
	global_store_short v147, v89, s[96:97] offset:2112
	global_store_short v148, v90, s[96:97]
	global_store_short v148, v91, s[96:97] offset:64
	global_store_short v148, v92, s[96:97] offset:2048
	global_store_short v148, v93, s[96:97] offset:2112
	global_store_short v149, v94, s[96:97]
	global_store_short v149, v95, s[96:97] offset:64
	global_store_short v149, v96, s[96:97] offset:2048
	global_store_short v149, v97, s[96:97] offset:2112
	global_store_short v150, v98, s[96:97]
	global_store_short v150, v99, s[96:97] offset:64
	global_store_short v150, v100, s[96:97] offset:2048
	global_store_short v150, v101, s[96:97] offset:2112
	global_store_short v151, v102, s[96:97]
	global_store_short v151, v103, s[96:97] offset:64
	global_store_short v151, v104, s[96:97] offset:2048
	global_store_short v151, v105, s[96:97] offset:2112
	global_store_short v152, v106, s[96:97]
	global_store_short v152, v107, s[96:97] offset:64
	global_store_short v152, v108, s[96:97] offset:2048
	global_store_short v152, v109, s[96:97] offset:2112
	global_store_short v153, v110, s[96:97]
	global_store_short v153, v111, s[96:97] offset:64
	global_store_short v153, v112, s[96:97] offset:2048
	global_store_short v153, v113, s[96:97] offset:2112
	global_store_short v154, v114, s[96:97]
	global_store_short v154, v115, s[96:97] offset:64
	global_store_short v154, v116, s[96:97] offset:2048
	global_store_short v154, v117, s[96:97] offset:2112
	global_store_short v155, v118, s[96:97]
	global_store_short v155, v119, s[96:97] offset:64
	global_store_short v155, v120, s[96:97] offset:2048
	global_store_short v155, v121, s[96:97] offset:2112
	global_store_short v156, v122, s[96:97]
	global_store_short v156, v123, s[96:97] offset:64
	global_store_short v156, v124, s[96:97] offset:2048
	global_store_short v156, v125, s[96:97] offset:2112
	global_store_short v157, v126, s[96:97]
	global_store_short v157, v127, s[96:97] offset:64
	global_store_short v157, v128, s[96:97] offset:2048
	global_store_short v157, v129, s[96:97] offset:2112
	global_store_short v158, v130, s[96:97]
	global_store_short v158, v131, s[96:97] offset:64
	global_store_short v158, v132, s[96:97] offset:2048
	global_store_short v158, v133, s[96:97] offset:2112
	global_store_short v159, v134, s[96:97]
	global_store_short v159, v135, s[96:97] offset:64
	global_store_short v159, v136, s[96:97] offset:2048
	global_store_short v159, v137, s[96:97] offset:2112
	global_store_short v160, v138, s[96:97]
	global_store_short v160, v139, s[96:97] offset:64
	global_store_short v160, v140, s[96:97] offset:2048
	global_store_short v160, v141, s[96:97] offset:2112
	global_store_short v161, v142, s[96:97]
	global_store_short v161, v143, s[96:97] offset:64
	global_store_short v161, v144, s[96:97] offset:2048
	global_store_short v161, v145, s[96:97] offset:2112
	s_mov_b64 s[6:7], 0
